# flash loops: removed the 13 conservative s_nop wait states that followed the last P.V MFMA of every tile body (no VALU reads the O accumulators within the hazard window on any path)
# speedup vs baseline: 1.0067x; 1.0067x over previous
; DI unsigned pack2(float a, float b) { f32x2 v = {a, b}; bf16x2_t r = __builtin_convertvector(v, bf16x2_t); return __builtin_bit_cast(unsigned, r); }
; DI f32x16 mfma32(bf16x8 a, bf16x8 b, f32x16 c) { return __builtin_amdgcn_mfma_f32_32x32x16_bf16(a, b, c, 0, 0, 0); }
;     ...
;   const float mn = fmaxf(m, mx); const float alpha = __builtin_amdgcn_exp2f(m - mn);
;   const float neg = (MODE == 2 && !lanesel) ? NINF : -mn;
;   float ps = 0.f;
; #pragma unroll
;   for (int k2 = 0; k2 < 2; ++k2)
; #pragma unroll
;     for (int i = 0; i < 16; ++i) {
;       if (!(HM & (1 << k2))) continue;
;       const float pv = (MODE == 1) ? __builtin_amdgcn_exp2f(s[k2][i] + neg) : __builtin_amdgcn_exp2f(fmaf(s[k2][i], L2E, neg));
;       s[k2][i] = pv; ps += pv;
;     }
;   l = l * alpha + ps;
;   if (__builtin_amdgcn_ballot_w64(mn != m) != 0ull) {
; #pragma unroll
;     for (int dt = 0; dt < 2; ++dt)
; #pragma unroll
;       for (int i = 0; i < 16; ++i) o[dt][i] *= alpha;
;   }
;   m = mn;
; #pragma unroll
;   for (int st = 0; st < 4; ++st) {
;     if (!(HM & (1 << (st >> 1)))) continue;
;     const int k2 = st >> 1, b8 = 8 * (st & 1);
;     const u32x4 pw = {pack2(s[k2][b8], s[k2][b8 + 1]), pack2(s[k2][b8 + 2], s[k2][b8 + 3]), pack2(s[k2][b8 + 4], s[k2][b8 + 5]), pack2(s[k2][b8 + 6], s[k2][b8 + 7])};
;     const bf16x8 pb = __builtin_bit_cast(bf16x8, pw);
; #pragma unroll
;     for (int dt = 0; dt < 2; ++dt) {
;       const s16x4 lo = *(const s16x4*)(Vs + (32 * dt + r) * LSTR + 16 * st + 4 * h);
;       const s16x4 hi = *(const s16x4*)(Vs + (32 * dt + r) * LSTR + 16 * st + 8 + 4 * h);
;       const bf16x8 a = __builtin_shufflevector(lo, hi, 0, 1, 2, 3, 4, 5, 6, 7);
;       o[dt] = mfma32(a, pb, o[dt]);
;     }
;   }
.LBB0_488:
	v_fma_f32 v34, v34, s34, -v158
	v_exp_f32_e32 v45, v34
	v_fma_f32 v34, v35, s34, -v158
	v_exp_f32_e32 v46, v34
	v_fma_f32 v34, v36, s34, -v158
	v_exp_f32_e32 v47, v34
	v_fma_f32 v34, v37, s34, -v158
	v_add_f32_e32 v35, 0, v45
	v_exp_f32_e32 v48, v34
	v_fma_f32 v34, v38, s34, -v158
	v_add_f32_e32 v35, v46, v35
	v_exp_f32_e32 v38, v34
	v_fma_f32 v34, v39, s34, -v158
	v_exp_f32_e32 v39, v34
	v_add_f32_e32 v34, v47, v35
	v_fma_f32 v35, v50, s34, -v158
	v_exp_f32_e32 v49, v35
	v_fma_f32 v35, v51, s34, -v158
	v_add_f32_e32 v34, v48, v34
	v_exp_f32_e32 v50, v35
	v_fma_f32 v35, v52, s34, -v158
	v_add_f32_e32 v34, v38, v34
	v_exp_f32_e32 v52, v35
	v_fma_f32 v35, v53, s34, -v158
	v_add_f32_e32 v34, v39, v34
	v_exp_f32_e32 v53, v35
	v_add_f32_e32 v34, v49, v34
	v_add_f32_e32 v34, v50, v34
	v_add_f32_e32 v34, v52, v34
	v_add_f32_e32 v55, v53, v34
	v_fma_f32 v34, v54, s34, -v158
	v_add_u32_e32 v56, 0x2000, v198
	v_exp_f32_e32 v54, v34
	ds_read2_b64 v[34:37], v56 offset0:128 offset1:130
	v_fma_f32 v44, v44, s34, -v158
	v_exp_f32_e32 v57, v44
	v_cvt_pk_bf16_f32 v44, v45, v46
	v_cvt_pk_bf16_f32 v46, v38, v39
	v_add_u32_e32 v38, 0x3000, v198
	v_cvt_pk_bf16_f32 v45, v47, v48
	v_cvt_pk_bf16_f32 v47, v49, v50
	ds_read2_b64 v[48:51], v38 offset0:192 offset1:194
	v_fma_f32 v39, v40, s34, -v158
	s_waitcnt lgkmcnt(1)
	v_mfma_f32_32x32x16_bf16 v[2:17], v[34:37], v[44:47], v[2:17]
	v_fma_f32 v34, v41, s34, -v158
	v_exp_f32_e32 v58, v34
	v_fma_f32 v34, v42, s34, -v158
	v_exp_f32_e32 v59, v34
	v_fma_f32 v34, v43, s34, -v158
	v_exp_f32_e32 v60, v34
	ds_read2_b64 v[34:37], v56 offset0:132 offset1:134
	s_waitcnt lgkmcnt(1)
	v_mfma_f32_32x32x16_bf16 v[18:33], v[48:51], v[44:47], v[18:33]
	v_exp_f32_e32 v46, v39
	ds_read2_b64 v[38:41], v38 offset0:196 offset1:198
	v_cvt_pk_bf16_f32 v42, v52, v53
	v_cvt_pk_bf16_f32 v43, v54, v57
	v_cvt_pk_bf16_f32 v44, v58, v59
	v_cvt_pk_bf16_f32 v45, v60, v46
	s_waitcnt lgkmcnt(0)
	s_nop 0
	v_mfma_f32_32x32x16_bf16 v[18:33], v[38:41], v[42:45], v[18:33]
	v_mfma_f32_32x32x16_bf16 v[2:17], v[34:37], v[42:45], v[2:17]
	v_add_f32_e32 v34, v54, v55
	v_add_f32_e32 v34, v57, v34
	v_add_f32_e32 v34, v58, v34
	v_add_f32_e32 v34, v59, v34
	v_add_f32_e32 v34, v60, v34
	v_add_f32_e32 v160, v46, v34
	s_nop 4
	v_fmac_f32_e32 v160, v159, v0
.LBB0_489:
	s_branch .LBB0_491
.LBB0_490:
	v_mov_b32_e32 v160, v159
	v_mov_b32_e32 v158, v157

; DI unsigned pack2(float a, float b) { f32x2 v = {a, b}; bf16x2_t r = __builtin_convertvector(v, bf16x2_t); return __builtin_bit_cast(unsigned, r); }
; DI f32x16 mfma32(bf16x8 a, bf16x8 b, f32x16 c) { return __builtin_amdgcn_mfma_f32_32x32x16_bf16(a, b, c, 0, 0, 0); }
;     ...
;   const float mn = fmaxf(m, mx); const float alpha = __builtin_amdgcn_exp2f(m - mn);
;   const float neg = (MODE == 2 && !lanesel) ? NINF : -mn;
;   float ps = 0.f;
; #pragma unroll
;   for (int k2 = 0; k2 < 2; ++k2)
; #pragma unroll
;     for (int i = 0; i < 16; ++i) {
;       if (!(HM & (1 << k2))) continue;
;       const float pv = (MODE == 1) ? __builtin_amdgcn_exp2f(s[k2][i] + neg) : __builtin_amdgcn_exp2f(fmaf(s[k2][i], L2E, neg));
;       s[k2][i] = pv; ps += pv;
;     }
;   l = l * alpha + ps;
;   if (__builtin_amdgcn_ballot_w64(mn != m) != 0ull) {
; #pragma unroll
;     for (int dt = 0; dt < 2; ++dt)
; #pragma unroll
;       for (int i = 0; i < 16; ++i) o[dt][i] *= alpha;
;   }
;   m = mn;
; #pragma unroll
;   for (int st = 0; st < 4; ++st) {
;     if (!(HM & (1 << (st >> 1)))) continue;
;     const int k2 = st >> 1, b8 = 8 * (st & 1);
;     const u32x4 pw = {pack2(s[k2][b8], s[k2][b8 + 1]), pack2(s[k2][b8 + 2], s[k2][b8 + 3]), pack2(s[k2][b8 + 4], s[k2][b8 + 5]), pack2(s[k2][b8 + 6], s[k2][b8 + 7])};
;     const bf16x8 pb = __builtin_bit_cast(bf16x8, pw);
; #pragma unroll
;     for (int dt = 0; dt < 2; ++dt) {
;       const s16x4 lo = *(const s16x4*)(Vs + (32 * dt + r) * LSTR + 16 * st + 4 * h);
;       const s16x4 hi = *(const s16x4*)(Vs + (32 * dt + r) * LSTR + 16 * st + 8 + 4 * h);
;       const bf16x8 a = __builtin_shufflevector(lo, hi, 0, 1, 2, 3, 4, 5, 6, 7);
;       o[dt] = mfma32(a, pb, o[dt]);
;     }
;   }
.LBB0_516:
	v_fma_f32 v34, v34, s34, -v157
	v_exp_f32_e32 v46, v34
	v_fma_f32 v34, v35, s34, -v157
	v_exp_f32_e32 v47, v34
	v_fma_f32 v34, v36, s34, -v157
	v_exp_f32_e32 v48, v34
	v_fma_f32 v34, v37, s34, -v157
	v_add_f32_e32 v35, 0, v46
	v_exp_f32_e32 v49, v34
	v_fma_f32 v34, v38, s34, -v157
	v_add_f32_e32 v35, v47, v35
	v_exp_f32_e32 v38, v34
	v_fma_f32 v34, v39, s34, -v157
	v_exp_f32_e32 v39, v34
	v_add_f32_e32 v34, v48, v35
	v_fma_f32 v35, v50, s34, -v157
	v_exp_f32_e32 v50, v35
	v_fma_f32 v35, v51, s34, -v157
	v_add_f32_e32 v34, v49, v34
	v_exp_f32_e32 v51, v35
	v_fma_f32 v35, v52, s34, -v157
	v_add_f32_e32 v34, v38, v34
	v_exp_f32_e32 v52, v35
	v_fma_f32 v35, v53, s34, -v157
	v_add_f32_e32 v34, v39, v34
	v_exp_f32_e32 v53, v35
	v_add_f32_e32 v34, v50, v34
	v_add_f32_e32 v34, v51, v34
	v_add_f32_e32 v34, v52, v34
	v_add_f32_e32 v54, v53, v34
	v_fma_f32 v34, v44, s34, -v157
	v_fma_f32 v44, v45, s34, -v157
	v_add_u32_e32 v56, 0x6800, v198
	v_exp_f32_e32 v55, v34
	ds_read2_b64 v[34:37], v56 offset0:128 offset1:130
	v_exp_f32_e32 v57, v44
	v_cvt_pk_bf16_f32 v44, v46, v47
	v_cvt_pk_bf16_f32 v46, v38, v39
	v_add_u32_e32 v38, v199, v200
	v_add_u32_e32 v38, 0x7800, v38
	v_cvt_pk_bf16_f32 v45, v48, v49
	v_cvt_pk_bf16_f32 v47, v50, v51
	ds_read2_b64 v[48:51], v38 offset0:192 offset1:194
	v_fma_f32 v39, v40, s34, -v157
	s_waitcnt lgkmcnt(1)
	v_mfma_f32_32x32x16_bf16 v[2:17], v[34:37], v[44:47], v[2:17]
	v_fma_f32 v34, v41, s34, -v157
	v_exp_f32_e32 v58, v34
	v_fma_f32 v34, v42, s34, -v157
	v_exp_f32_e32 v59, v34
	v_fma_f32 v34, v43, s34, -v157
	v_exp_f32_e32 v60, v34
	ds_read2_b64 v[34:37], v56 offset0:132 offset1:134
	s_waitcnt lgkmcnt(1)
	v_mfma_f32_32x32x16_bf16 v[18:33], v[48:51], v[44:47], v[18:33]
	v_exp_f32_e32 v46, v39
	ds_read2_b64 v[38:41], v38 offset0:196 offset1:198
	v_cvt_pk_bf16_f32 v42, v52, v53
	v_cvt_pk_bf16_f32 v43, v55, v57
	v_cvt_pk_bf16_f32 v44, v58, v59
	v_cvt_pk_bf16_f32 v45, v60, v46
	s_waitcnt lgkmcnt(0)
	s_nop 0
	v_mfma_f32_32x32x16_bf16 v[18:33], v[38:41], v[42:45], v[18:33]
	v_mfma_f32_32x32x16_bf16 v[2:17], v[34:37], v[42:45], v[2:17]
	v_add_f32_e32 v34, v55, v54
	v_add_f32_e32 v34, v57, v34
	v_add_f32_e32 v34, v58, v34
	v_add_f32_e32 v34, v59, v34
	v_add_f32_e32 v34, v60, v34
	v_add_f32_e32 v159, v46, v34
	s_nop 4
	v_fmac_f32_e32 v159, v160, v0
.LBB0_517:
	s_branch .LBB0_519
.LBB0_518:
	v_mov_b32_e32 v159, v160
	v_mov_b32_e32 v157, v158

; DI unsigned pack2(float a, float b) { f32x2 v = {a, b}; bf16x2_t r = __builtin_convertvector(v, bf16x2_t); return __builtin_bit_cast(unsigned, r); }
; DI f32x16 mfma32(bf16x8 a, bf16x8 b, f32x16 c) { return __builtin_amdgcn_mfma_f32_32x32x16_bf16(a, b, c, 0, 0, 0); }
;     ...
;   const float mn = fmaxf(m, mx); const float alpha = __builtin_amdgcn_exp2f(m - mn);
;   const float neg = (MODE == 2 && !lanesel) ? NINF : -mn;
;   float ps = 0.f;
; #pragma unroll
;   for (int k2 = 0; k2 < 2; ++k2)
; #pragma unroll
;     for (int i = 0; i < 16; ++i) {
;       if (!(HM & (1 << k2))) continue;
;       const float pv = (MODE == 1) ? __builtin_amdgcn_exp2f(s[k2][i] + neg) : __builtin_amdgcn_exp2f(fmaf(s[k2][i], L2E, neg));
;       s[k2][i] = pv; ps += pv;
;     }
;   l = l * alpha + ps;
;   if (__builtin_amdgcn_ballot_w64(mn != m) != 0ull) {
; #pragma unroll
;     for (int dt = 0; dt < 2; ++dt)
; #pragma unroll
;       for (int i = 0; i < 16; ++i) o[dt][i] *= alpha;
;   }
;   m = mn;
; #pragma unroll
;   for (int st = 0; st < 4; ++st) {
;     if (!(HM & (1 << (st >> 1)))) continue;
;     const int k2 = st >> 1, b8 = 8 * (st & 1);
;     const u32x4 pw = {pack2(s[k2][b8], s[k2][b8 + 1]), pack2(s[k2][b8 + 2], s[k2][b8 + 3]), pack2(s[k2][b8 + 4], s[k2][b8 + 5]), pack2(s[k2][b8 + 6], s[k2][b8 + 7])};
;     const bf16x8 pb = __builtin_bit_cast(bf16x8, pw);
; #pragma unroll
;     for (int dt = 0; dt < 2; ++dt) {
;       const s16x4 lo = *(const s16x4*)(Vs + (32 * dt + r) * LSTR + 16 * st + 4 * h);
;       const s16x4 hi = *(const s16x4*)(Vs + (32 * dt + r) * LSTR + 16 * st + 8 + 4 * h);
;       const bf16x8 a = __builtin_shufflevector(lo, hi, 0, 1, 2, 3, 4, 5, 6, 7);
;       o[dt] = mfma32(a, pb, o[dt]);
;     }
;   }
.LBB0_552:
	v_fma_f32 v34, v34, s34, -v158
	v_exp_f32_e32 v45, v34
	v_fma_f32 v34, v35, s34, -v158
	v_exp_f32_e32 v46, v34
	v_fma_f32 v34, v36, s34, -v158
	v_exp_f32_e32 v47, v34
	v_fma_f32 v34, v37, s34, -v158
	v_add_f32_e32 v35, 0, v45
	v_exp_f32_e32 v48, v34
	v_fma_f32 v34, v38, s34, -v158
	v_add_f32_e32 v35, v46, v35
	v_exp_f32_e32 v38, v34
	v_fma_f32 v34, v39, s34, -v158
	v_exp_f32_e32 v39, v34
	v_add_f32_e32 v34, v47, v35
	v_fma_f32 v35, v50, s34, -v158
	v_exp_f32_e32 v49, v35
	v_fma_f32 v35, v51, s34, -v158
	v_add_f32_e32 v34, v48, v34
	v_exp_f32_e32 v50, v35
	v_fma_f32 v35, v52, s34, -v158
	v_add_f32_e32 v34, v38, v34
	v_exp_f32_e32 v52, v35
	v_fma_f32 v35, v53, s34, -v158
	v_add_f32_e32 v34, v39, v34
	v_exp_f32_e32 v53, v35
	v_add_f32_e32 v34, v49, v34
	v_add_f32_e32 v34, v50, v34
	v_add_f32_e32 v34, v52, v34
	v_add_f32_e32 v55, v53, v34
	v_fma_f32 v34, v54, s34, -v158
	v_add_u32_e32 v56, 0x2000, v198
	v_exp_f32_e32 v54, v34
	ds_read2_b64 v[34:37], v56 offset0:128 offset1:130
	v_fma_f32 v44, v44, s34, -v158
	v_exp_f32_e32 v57, v44
	v_cvt_pk_bf16_f32 v44, v45, v46
	v_cvt_pk_bf16_f32 v46, v38, v39
	v_add_u32_e32 v38, 0x3000, v198
	v_cvt_pk_bf16_f32 v45, v47, v48
	v_cvt_pk_bf16_f32 v47, v49, v50
	ds_read2_b64 v[48:51], v38 offset0:192 offset1:194
	v_fma_f32 v39, v40, s34, -v158
	s_waitcnt lgkmcnt(1)
	v_mfma_f32_32x32x16_bf16 v[2:17], v[34:37], v[44:47], v[2:17]
	v_fma_f32 v34, v41, s34, -v158
	v_exp_f32_e32 v58, v34
	v_fma_f32 v34, v42, s34, -v158
	v_exp_f32_e32 v59, v34
	v_fma_f32 v34, v43, s34, -v158
	v_exp_f32_e32 v60, v34
	ds_read2_b64 v[34:37], v56 offset0:132 offset1:134
	s_waitcnt lgkmcnt(1)
	v_mfma_f32_32x32x16_bf16 v[18:33], v[48:51], v[44:47], v[18:33]
	v_exp_f32_e32 v46, v39
	ds_read2_b64 v[38:41], v38 offset0:196 offset1:198
	v_cvt_pk_bf16_f32 v42, v52, v53
	v_cvt_pk_bf16_f32 v43, v54, v57
	v_cvt_pk_bf16_f32 v44, v58, v59
	v_cvt_pk_bf16_f32 v45, v60, v46
	s_waitcnt lgkmcnt(0)
	s_nop 0
	v_mfma_f32_32x32x16_bf16 v[18:33], v[38:41], v[42:45], v[18:33]
	v_mfma_f32_32x32x16_bf16 v[2:17], v[34:37], v[42:45], v[2:17]
	v_add_f32_e32 v34, v54, v55
	v_add_f32_e32 v34, v57, v34
	v_add_f32_e32 v34, v58, v34
	v_add_f32_e32 v34, v59, v34
	v_add_f32_e32 v34, v60, v34
	v_add_f32_e32 v160, v46, v34
	s_nop 4
	v_fmac_f32_e32 v160, v159, v0
.LBB0_553:
	s_branch .LBB0_555
.LBB0_554:
	v_mov_b32_e32 v160, v159
	v_mov_b32_e32 v158, v157

; DI unsigned pack2(float a, float b) { f32x2 v = {a, b}; bf16x2_t r = __builtin_convertvector(v, bf16x2_t); return __builtin_bit_cast(unsigned, r); }
; DI f32x16 mfma32(bf16x8 a, bf16x8 b, f32x16 c) { return __builtin_amdgcn_mfma_f32_32x32x16_bf16(a, b, c, 0, 0, 0); }
;     ...
;   const float mn = fmaxf(m, mx); const float alpha = __builtin_amdgcn_exp2f(m - mn);
;   const float neg = (MODE == 2 && !lanesel) ? NINF : -mn;
;   float ps = 0.f;
; #pragma unroll
;   for (int k2 = 0; k2 < 2; ++k2)
; #pragma unroll
;     for (int i = 0; i < 16; ++i) {
;       if (!(HM & (1 << k2))) continue;
;       const float pv = (MODE == 1) ? __builtin_amdgcn_exp2f(s[k2][i] + neg) : __builtin_amdgcn_exp2f(fmaf(s[k2][i], L2E, neg));
;       s[k2][i] = pv; ps += pv;
;     }
;   l = l * alpha + ps;
;   if (__builtin_amdgcn_ballot_w64(mn != m) != 0ull) {
; #pragma unroll
;     for (int dt = 0; dt < 2; ++dt)
; #pragma unroll
;       for (int i = 0; i < 16; ++i) o[dt][i] *= alpha;
;   }
;   m = mn;
; #pragma unroll
;   for (int st = 0; st < 4; ++st) {
;     if (!(HM & (1 << (st >> 1)))) continue;
;     const int k2 = st >> 1, b8 = 8 * (st & 1);
;     const u32x4 pw = {pack2(s[k2][b8], s[k2][b8 + 1]), pack2(s[k2][b8 + 2], s[k2][b8 + 3]), pack2(s[k2][b8 + 4], s[k2][b8 + 5]), pack2(s[k2][b8 + 6], s[k2][b8 + 7])};
;     const bf16x8 pb = __builtin_bit_cast(bf16x8, pw);
; #pragma unroll
;     for (int dt = 0; dt < 2; ++dt) {
;       const s16x4 lo = *(const s16x4*)(Vs + (32 * dt + r) * LSTR + 16 * st + 4 * h);
;       const s16x4 hi = *(const s16x4*)(Vs + (32 * dt + r) * LSTR + 16 * st + 8 + 4 * h);
;       const bf16x8 a = __builtin_shufflevector(lo, hi, 0, 1, 2, 3, 4, 5, 6, 7);
;       o[dt] = mfma32(a, pb, o[dt]);
;     }
;   }
.LBB0_580:
	v_fma_f32 v34, v34, s34, -v157
	v_exp_f32_e32 v46, v34
	v_fma_f32 v34, v35, s34, -v157
	v_exp_f32_e32 v47, v34
	v_fma_f32 v34, v36, s34, -v157
	v_exp_f32_e32 v48, v34
	v_fma_f32 v34, v37, s34, -v157
	v_add_f32_e32 v35, 0, v46
	v_exp_f32_e32 v49, v34
	v_fma_f32 v34, v38, s34, -v157
	v_add_f32_e32 v35, v47, v35
	v_exp_f32_e32 v38, v34
	v_fma_f32 v34, v39, s34, -v157
	v_exp_f32_e32 v39, v34
	v_add_f32_e32 v34, v48, v35
	v_fma_f32 v35, v50, s34, -v157
	v_exp_f32_e32 v50, v35
	v_fma_f32 v35, v51, s34, -v157
	v_add_f32_e32 v34, v49, v34
	v_exp_f32_e32 v51, v35
	v_fma_f32 v35, v52, s34, -v157
	v_add_f32_e32 v34, v38, v34
	v_exp_f32_e32 v52, v35
	v_fma_f32 v35, v53, s34, -v157
	v_add_f32_e32 v34, v39, v34
	v_exp_f32_e32 v53, v35
	v_add_f32_e32 v34, v50, v34
	v_add_f32_e32 v34, v51, v34
	v_add_f32_e32 v34, v52, v34
	v_add_f32_e32 v54, v53, v34
	v_fma_f32 v34, v44, s34, -v157
	v_fma_f32 v44, v45, s34, -v157
	v_add_u32_e32 v56, 0x6800, v198
	v_exp_f32_e32 v55, v34
	ds_read2_b64 v[34:37], v56 offset0:128 offset1:130
	v_exp_f32_e32 v57, v44
	v_cvt_pk_bf16_f32 v44, v46, v47
	v_cvt_pk_bf16_f32 v46, v38, v39
	v_add_u32_e32 v38, v199, v200
	v_add_u32_e32 v38, 0x7800, v38
	v_cvt_pk_bf16_f32 v45, v48, v49
	v_cvt_pk_bf16_f32 v47, v50, v51
	ds_read2_b64 v[48:51], v38 offset0:192 offset1:194
	v_fma_f32 v39, v40, s34, -v157
	s_waitcnt lgkmcnt(1)
	v_mfma_f32_32x32x16_bf16 v[2:17], v[34:37], v[44:47], v[2:17]
	v_fma_f32 v34, v41, s34, -v157
	v_exp_f32_e32 v58, v34
	v_fma_f32 v34, v42, s34, -v157
	v_exp_f32_e32 v59, v34
	v_fma_f32 v34, v43, s34, -v157
	v_exp_f32_e32 v60, v34
	ds_read2_b64 v[34:37], v56 offset0:132 offset1:134
	s_waitcnt lgkmcnt(1)
	v_mfma_f32_32x32x16_bf16 v[18:33], v[48:51], v[44:47], v[18:33]
	v_exp_f32_e32 v46, v39
	ds_read2_b64 v[38:41], v38 offset0:196 offset1:198
	v_cvt_pk_bf16_f32 v42, v52, v53
	v_cvt_pk_bf16_f32 v43, v55, v57
	v_cvt_pk_bf16_f32 v44, v58, v59
	v_cvt_pk_bf16_f32 v45, v60, v46
	s_waitcnt lgkmcnt(0)
	s_nop 0
	v_mfma_f32_32x32x16_bf16 v[18:33], v[38:41], v[42:45], v[18:33]
	v_mfma_f32_32x32x16_bf16 v[2:17], v[34:37], v[42:45], v[2:17]
	v_add_f32_e32 v34, v55, v54
	v_add_f32_e32 v34, v57, v34
	v_add_f32_e32 v34, v58, v34
	v_add_f32_e32 v34, v59, v34
	v_add_f32_e32 v34, v60, v34
	v_add_f32_e32 v159, v46, v34
	s_nop 4
	v_fmac_f32_e32 v159, v160, v0
.LBB0_581:
	s_branch .LBB0_583
.LBB0_582:
	v_mov_b32_e32 v159, v160
	v_mov_b32_e32 v157, v158

; DI unsigned pack2(float a, float b) { f32x2 v = {a, b}; bf16x2_t r = __builtin_convertvector(v, bf16x2_t); return __builtin_bit_cast(unsigned, r); }
; DI f32x16 mfma32(bf16x8 a, bf16x8 b, f32x16 c) { return __builtin_amdgcn_mfma_f32_32x32x16_bf16(a, b, c, 0, 0, 0); }
;     ...
;   const float mn = fmaxf(m, mx); const float alpha = __builtin_amdgcn_exp2f(m - mn);
;   const float neg = (MODE == 2 && !lanesel) ? NINF : -mn;
;   float ps = 0.f;
; #pragma unroll
;   for (int k2 = 0; k2 < 2; ++k2)
; #pragma unroll
;     for (int i = 0; i < 16; ++i) {
;       if (!(HM & (1 << k2))) continue;
;       const float pv = (MODE == 1) ? __builtin_amdgcn_exp2f(s[k2][i] + neg) : __builtin_amdgcn_exp2f(fmaf(s[k2][i], L2E, neg));
;       s[k2][i] = pv; ps += pv;
;     }
;   l = l * alpha + ps;
;   if (__builtin_amdgcn_ballot_w64(mn != m) != 0ull) {
; #pragma unroll
;     for (int dt = 0; dt < 2; ++dt)
; #pragma unroll
;       for (int i = 0; i < 16; ++i) o[dt][i] *= alpha;
;   }
;   m = mn;
; #pragma unroll
;   for (int st = 0; st < 4; ++st) {
;     if (!(HM & (1 << (st >> 1)))) continue;
;     const int k2 = st >> 1, b8 = 8 * (st & 1);
;     const u32x4 pw = {pack2(s[k2][b8], s[k2][b8 + 1]), pack2(s[k2][b8 + 2], s[k2][b8 + 3]), pack2(s[k2][b8 + 4], s[k2][b8 + 5]), pack2(s[k2][b8 + 6], s[k2][b8 + 7])};
;     const bf16x8 pb = __builtin_bit_cast(bf16x8, pw);
; #pragma unroll
;     for (int dt = 0; dt < 2; ++dt) {
;       const s16x4 lo = *(const s16x4*)(Vs + (32 * dt + r) * LSTR + 16 * st + 4 * h);
;       const s16x4 hi = *(const s16x4*)(Vs + (32 * dt + r) * LSTR + 16 * st + 8 + 4 * h);
;       const bf16x8 a = __builtin_shufflevector(lo, hi, 0, 1, 2, 3, 4, 5, 6, 7);
;       o[dt] = mfma32(a, pb, o[dt]);
;     }
;   }
.LBB0_616:
	v_fma_f32 v34, v34, s34, -v158
	v_exp_f32_e32 v45, v34
	v_fma_f32 v34, v35, s34, -v158
	v_exp_f32_e32 v46, v34
	v_fma_f32 v34, v36, s34, -v158
	v_exp_f32_e32 v47, v34
	v_fma_f32 v34, v37, s34, -v158
	v_add_f32_e32 v35, 0, v45
	v_exp_f32_e32 v48, v34
	v_fma_f32 v34, v38, s34, -v158
	v_add_f32_e32 v35, v46, v35
	v_exp_f32_e32 v38, v34
	v_fma_f32 v34, v39, s34, -v158
	v_exp_f32_e32 v39, v34
	v_add_f32_e32 v34, v47, v35
	v_fma_f32 v35, v50, s34, -v158
	v_exp_f32_e32 v49, v35
	v_fma_f32 v35, v51, s34, -v158
	v_add_f32_e32 v34, v48, v34
	v_exp_f32_e32 v50, v35
	v_fma_f32 v35, v52, s34, -v158
	v_add_f32_e32 v34, v38, v34
	v_exp_f32_e32 v52, v35
	v_fma_f32 v35, v53, s34, -v158
	v_add_f32_e32 v34, v39, v34
	v_exp_f32_e32 v53, v35
	v_add_f32_e32 v34, v49, v34
	v_add_f32_e32 v34, v50, v34
	v_add_f32_e32 v34, v52, v34
	v_add_f32_e32 v55, v53, v34
	v_fma_f32 v34, v54, s34, -v158
	v_add_u32_e32 v56, 0x2000, v198
	v_exp_f32_e32 v54, v34
	ds_read2_b64 v[34:37], v56 offset0:128 offset1:130
	v_fma_f32 v44, v44, s34, -v158
	v_exp_f32_e32 v57, v44
	v_cvt_pk_bf16_f32 v44, v45, v46
	v_cvt_pk_bf16_f32 v46, v38, v39
	v_add_u32_e32 v38, 0x3000, v198
	v_cvt_pk_bf16_f32 v45, v47, v48
	v_cvt_pk_bf16_f32 v47, v49, v50
	ds_read2_b64 v[48:51], v38 offset0:192 offset1:194
	v_fma_f32 v39, v40, s34, -v158
	s_waitcnt lgkmcnt(1)
	v_mfma_f32_32x32x16_bf16 v[2:17], v[34:37], v[44:47], v[2:17]
	v_fma_f32 v34, v41, s34, -v158
	v_exp_f32_e32 v58, v34
	v_fma_f32 v34, v42, s34, -v158
	v_exp_f32_e32 v59, v34
	v_fma_f32 v34, v43, s34, -v158
	v_exp_f32_e32 v60, v34
	ds_read2_b64 v[34:37], v56 offset0:132 offset1:134
	s_waitcnt lgkmcnt(1)
	v_mfma_f32_32x32x16_bf16 v[18:33], v[48:51], v[44:47], v[18:33]
	v_exp_f32_e32 v46, v39
	ds_read2_b64 v[38:41], v38 offset0:196 offset1:198
	v_cvt_pk_bf16_f32 v42, v52, v53
	v_cvt_pk_bf16_f32 v43, v54, v57
	v_cvt_pk_bf16_f32 v44, v58, v59
	v_cvt_pk_bf16_f32 v45, v60, v46
	s_waitcnt lgkmcnt(0)
	s_nop 0
	v_mfma_f32_32x32x16_bf16 v[18:33], v[38:41], v[42:45], v[18:33]
	v_mfma_f32_32x32x16_bf16 v[2:17], v[34:37], v[42:45], v[2:17]
	v_add_f32_e32 v34, v54, v55
	v_add_f32_e32 v34, v57, v34
	v_add_f32_e32 v34, v58, v34
	v_add_f32_e32 v34, v59, v34
	v_add_f32_e32 v34, v60, v34
	v_add_f32_e32 v160, v46, v34
	s_nop 4
	v_fmac_f32_e32 v160, v159, v0
.LBB0_617:
	s_branch .LBB0_619
.LBB0_618:
	v_mov_b32_e32 v160, v159
	v_mov_b32_e32 v158, v157

; DI unsigned pack2(float a, float b) { f32x2 v = {a, b}; bf16x2_t r = __builtin_convertvector(v, bf16x2_t); return __builtin_bit_cast(unsigned, r); }
; DI f32x16 mfma32(bf16x8 a, bf16x8 b, f32x16 c) { return __builtin_amdgcn_mfma_f32_32x32x16_bf16(a, b, c, 0, 0, 0); }
;     ...
;   const float mn = fmaxf(m, mx); const float alpha = __builtin_amdgcn_exp2f(m - mn);
;   const float neg = (MODE == 2 && !lanesel) ? NINF : -mn;
;   float ps = 0.f;
; #pragma unroll
;   for (int k2 = 0; k2 < 2; ++k2)
; #pragma unroll
;     for (int i = 0; i < 16; ++i) {
;       if (!(HM & (1 << k2))) continue;
;       const float pv = (MODE == 1) ? __builtin_amdgcn_exp2f(s[k2][i] + neg) : __builtin_amdgcn_exp2f(fmaf(s[k2][i], L2E, neg));
;       s[k2][i] = pv; ps += pv;
;     }
;   l = l * alpha + ps;
;   if (__builtin_amdgcn_ballot_w64(mn != m) != 0ull) {
; #pragma unroll
;     for (int dt = 0; dt < 2; ++dt)
; #pragma unroll
;       for (int i = 0; i < 16; ++i) o[dt][i] *= alpha;
;   }
;   m = mn;
; #pragma unroll
;   for (int st = 0; st < 4; ++st) {
;     if (!(HM & (1 << (st >> 1)))) continue;
;     const int k2 = st >> 1, b8 = 8 * (st & 1);
;     const u32x4 pw = {pack2(s[k2][b8], s[k2][b8 + 1]), pack2(s[k2][b8 + 2], s[k2][b8 + 3]), pack2(s[k2][b8 + 4], s[k2][b8 + 5]), pack2(s[k2][b8 + 6], s[k2][b8 + 7])};
;     const bf16x8 pb = __builtin_bit_cast(bf16x8, pw);
; #pragma unroll
;     for (int dt = 0; dt < 2; ++dt) {
;       const s16x4 lo = *(const s16x4*)(Vs + (32 * dt + r) * LSTR + 16 * st + 4 * h);
;       const s16x4 hi = *(const s16x4*)(Vs + (32 * dt + r) * LSTR + 16 * st + 8 + 4 * h);
;       const bf16x8 a = __builtin_shufflevector(lo, hi, 0, 1, 2, 3, 4, 5, 6, 7);
;       o[dt] = mfma32(a, pb, o[dt]);
;     }
;   }
.LBB0_644:
	v_fma_f32 v34, v34, s34, -v157
	v_exp_f32_e32 v46, v34
	v_fma_f32 v34, v35, s34, -v157
	v_exp_f32_e32 v47, v34
	v_fma_f32 v34, v36, s34, -v157
	v_exp_f32_e32 v48, v34
	v_fma_f32 v34, v37, s34, -v157
	v_add_f32_e32 v35, 0, v46
	v_exp_f32_e32 v49, v34
	v_fma_f32 v34, v38, s34, -v157
	v_add_f32_e32 v35, v47, v35
	v_exp_f32_e32 v38, v34
	v_fma_f32 v34, v39, s34, -v157
	v_exp_f32_e32 v39, v34
	v_add_f32_e32 v34, v48, v35
	v_fma_f32 v35, v50, s34, -v157
	v_exp_f32_e32 v50, v35
	v_fma_f32 v35, v51, s34, -v157
	v_add_f32_e32 v34, v49, v34
	v_exp_f32_e32 v51, v35
	v_fma_f32 v35, v52, s34, -v157
	v_add_f32_e32 v34, v38, v34
	v_exp_f32_e32 v52, v35
	v_fma_f32 v35, v53, s34, -v157
	v_add_f32_e32 v34, v39, v34
	v_exp_f32_e32 v53, v35
	v_add_f32_e32 v34, v50, v34
	v_add_f32_e32 v34, v51, v34
	v_add_f32_e32 v34, v52, v34
	v_add_f32_e32 v54, v53, v34
	v_fma_f32 v34, v44, s34, -v157
	v_fma_f32 v44, v45, s34, -v157
	v_add_u32_e32 v56, 0x6800, v198
	v_exp_f32_e32 v55, v34
	ds_read2_b64 v[34:37], v56 offset0:128 offset1:130
	v_exp_f32_e32 v57, v44
	v_cvt_pk_bf16_f32 v44, v46, v47
	v_cvt_pk_bf16_f32 v46, v38, v39
	v_add_u32_e32 v38, v199, v200
	v_add_u32_e32 v38, 0x7800, v38
	v_cvt_pk_bf16_f32 v45, v48, v49
	v_cvt_pk_bf16_f32 v47, v50, v51
	ds_read2_b64 v[48:51], v38 offset0:192 offset1:194
	v_fma_f32 v39, v40, s34, -v157
	s_waitcnt lgkmcnt(1)
	v_mfma_f32_32x32x16_bf16 v[2:17], v[34:37], v[44:47], v[2:17]
	v_fma_f32 v34, v41, s34, -v157
	v_exp_f32_e32 v58, v34
	v_fma_f32 v34, v42, s34, -v157
	v_exp_f32_e32 v59, v34
	v_fma_f32 v34, v43, s34, -v157
	v_exp_f32_e32 v60, v34
	ds_read2_b64 v[34:37], v56 offset0:132 offset1:134
	s_waitcnt lgkmcnt(1)
	v_mfma_f32_32x32x16_bf16 v[18:33], v[48:51], v[44:47], v[18:33]
	v_exp_f32_e32 v46, v39
	ds_read2_b64 v[38:41], v38 offset0:196 offset1:198
	v_cvt_pk_bf16_f32 v42, v52, v53
	v_cvt_pk_bf16_f32 v43, v55, v57
	v_cvt_pk_bf16_f32 v44, v58, v59
	v_cvt_pk_bf16_f32 v45, v60, v46
	s_waitcnt lgkmcnt(0)
	s_nop 0
	v_mfma_f32_32x32x16_bf16 v[18:33], v[38:41], v[42:45], v[18:33]
	v_mfma_f32_32x32x16_bf16 v[2:17], v[34:37], v[42:45], v[2:17]
	v_add_f32_e32 v34, v55, v54
	v_add_f32_e32 v34, v57, v34
	v_add_f32_e32 v34, v58, v34
	v_add_f32_e32 v34, v59, v34
	v_add_f32_e32 v34, v60, v34
	v_add_f32_e32 v159, v46, v34
	s_nop 4
	v_fmac_f32_e32 v159, v160, v0
.LBB0_645:
	s_branch .LBB0_647
.LBB0_646:
	v_mov_b32_e32 v159, v160
	v_mov_b32_e32 v157, v158

; DI unsigned pack2(float a, float b) { f32x2 v = {a, b}; bf16x2_t r = __builtin_convertvector(v, bf16x2_t); return __builtin_bit_cast(unsigned, r); }
; DI f32x16 mfma32(bf16x8 a, bf16x8 b, f32x16 c) { return __builtin_amdgcn_mfma_f32_32x32x16_bf16(a, b, c, 0, 0, 0); }
;     ...
;   const float mn = fmaxf(m, mx); const float alpha = __builtin_amdgcn_exp2f(m - mn);
;   const float neg = (MODE == 2 && !lanesel) ? NINF : -mn;
;   float ps = 0.f;
; #pragma unroll
;   for (int k2 = 0; k2 < 2; ++k2)
; #pragma unroll
;     for (int i = 0; i < 16; ++i) {
;       if (!(HM & (1 << k2))) continue;
;       const float pv = (MODE == 1) ? __builtin_amdgcn_exp2f(s[k2][i] + neg) : __builtin_amdgcn_exp2f(fmaf(s[k2][i], L2E, neg));
;       s[k2][i] = pv; ps += pv;
;     }
;   l = l * alpha + ps;
;   if (__builtin_amdgcn_ballot_w64(mn != m) != 0ull) {
; #pragma unroll
;     for (int dt = 0; dt < 2; ++dt)
; #pragma unroll
;       for (int i = 0; i < 16; ++i) o[dt][i] *= alpha;
;   }
;   m = mn;
; #pragma unroll
;   for (int st = 0; st < 4; ++st) {
;     if (!(HM & (1 << (st >> 1)))) continue;
;     const int k2 = st >> 1, b8 = 8 * (st & 1);
;     const u32x4 pw = {pack2(s[k2][b8], s[k2][b8 + 1]), pack2(s[k2][b8 + 2], s[k2][b8 + 3]), pack2(s[k2][b8 + 4], s[k2][b8 + 5]), pack2(s[k2][b8 + 6], s[k2][b8 + 7])};
;     const bf16x8 pb = __builtin_bit_cast(bf16x8, pw);
; #pragma unroll
;     for (int dt = 0; dt < 2; ++dt) {
;       const s16x4 lo = *(const s16x4*)(Vs + (32 * dt + r) * LSTR + 16 * st + 4 * h);
;       const s16x4 hi = *(const s16x4*)(Vs + (32 * dt + r) * LSTR + 16 * st + 8 + 4 * h);
;       const bf16x8 a = __builtin_shufflevector(lo, hi, 0, 1, 2, 3, 4, 5, 6, 7);
;       o[dt] = mfma32(a, pb, o[dt]);
;     }
;   }
.LBB0_684:
	v_fma_f32 v34, v34, s34, -v158
	v_exp_f32_e32 v45, v34
	v_fma_f32 v34, v35, s34, -v158
	v_exp_f32_e32 v46, v34
	v_fma_f32 v34, v36, s34, -v158
	v_exp_f32_e32 v47, v34
	v_fma_f32 v34, v37, s34, -v158
	v_add_f32_e32 v35, 0, v45
	v_exp_f32_e32 v48, v34
	v_fma_f32 v34, v38, s34, -v158
	v_add_f32_e32 v35, v46, v35
	v_exp_f32_e32 v38, v34
	v_fma_f32 v34, v39, s34, -v158
	v_exp_f32_e32 v39, v34
	v_add_f32_e32 v34, v47, v35
	v_fma_f32 v35, v50, s34, -v158
	v_exp_f32_e32 v49, v35
	v_fma_f32 v35, v51, s34, -v158
	v_add_f32_e32 v34, v48, v34
	v_exp_f32_e32 v50, v35
	v_fma_f32 v35, v52, s34, -v158
	v_add_f32_e32 v34, v38, v34
	v_exp_f32_e32 v52, v35
	v_fma_f32 v35, v53, s34, -v158
	v_add_f32_e32 v34, v39, v34
	v_exp_f32_e32 v53, v35
	v_add_f32_e32 v34, v49, v34
	v_add_f32_e32 v34, v50, v34
	v_add_f32_e32 v34, v52, v34
	v_add_f32_e32 v55, v53, v34
	v_fma_f32 v34, v54, s34, -v158
	v_add_u32_e32 v56, 0x2000, v198
	v_exp_f32_e32 v54, v34
	ds_read2_b64 v[34:37], v56 offset0:128 offset1:130
	v_fma_f32 v44, v44, s34, -v158
	v_exp_f32_e32 v57, v44
	v_cvt_pk_bf16_f32 v44, v45, v46
	v_cvt_pk_bf16_f32 v46, v38, v39
	v_add_u32_e32 v38, 0x3000, v198
	v_cvt_pk_bf16_f32 v45, v47, v48
	v_cvt_pk_bf16_f32 v47, v49, v50
	ds_read2_b64 v[48:51], v38 offset0:192 offset1:194
	v_fma_f32 v39, v40, s34, -v158
	s_waitcnt lgkmcnt(1)
	v_mfma_f32_32x32x16_bf16 v[2:17], v[34:37], v[44:47], v[2:17]
	v_fma_f32 v34, v41, s34, -v158
	v_exp_f32_e32 v58, v34
	v_fma_f32 v34, v42, s34, -v158
	v_exp_f32_e32 v59, v34
	v_fma_f32 v34, v43, s34, -v158
	v_exp_f32_e32 v60, v34
	ds_read2_b64 v[34:37], v56 offset0:132 offset1:134
	s_waitcnt lgkmcnt(1)
	v_mfma_f32_32x32x16_bf16 v[18:33], v[48:51], v[44:47], v[18:33]
	v_exp_f32_e32 v46, v39
	ds_read2_b64 v[38:41], v38 offset0:196 offset1:198
	v_cvt_pk_bf16_f32 v42, v52, v53
	v_cvt_pk_bf16_f32 v43, v54, v57
	v_cvt_pk_bf16_f32 v44, v58, v59
	v_cvt_pk_bf16_f32 v45, v60, v46
	s_waitcnt lgkmcnt(0)
	s_nop 0
	v_mfma_f32_32x32x16_bf16 v[18:33], v[38:41], v[42:45], v[18:33]
	v_mfma_f32_32x32x16_bf16 v[2:17], v[34:37], v[42:45], v[2:17]
	v_add_f32_e32 v34, v54, v55
	v_add_f32_e32 v34, v57, v34
	v_add_f32_e32 v34, v58, v34
	v_add_f32_e32 v34, v59, v34
	v_add_f32_e32 v34, v60, v34
	v_add_f32_e32 v160, v46, v34
	s_nop 4
	v_fmac_f32_e32 v160, v159, v0
.LBB0_685:
	s_branch .LBB0_687
.LBB0_686:
	v_mov_b32_e32 v160, v159
	v_mov_b32_e32 v158, v157

; DI unsigned pack2(float a, float b) { f32x2 v = {a, b}; bf16x2_t r = __builtin_convertvector(v, bf16x2_t); return __builtin_bit_cast(unsigned, r); }
; DI f32x16 mfma32(bf16x8 a, bf16x8 b, f32x16 c) { return __builtin_amdgcn_mfma_f32_32x32x16_bf16(a, b, c, 0, 0, 0); }
;     ...
;   const float mn = fmaxf(m, mx); const float alpha = __builtin_amdgcn_exp2f(m - mn);
;   const float neg = (MODE == 2 && !lanesel) ? NINF : -mn;
;   float ps = 0.f;
; #pragma unroll
;   for (int k2 = 0; k2 < 2; ++k2)
; #pragma unroll
;     for (int i = 0; i < 16; ++i) {
;       if (!(HM & (1 << k2))) continue;
;       const float pv = (MODE == 1) ? __builtin_amdgcn_exp2f(s[k2][i] + neg) : __builtin_amdgcn_exp2f(fmaf(s[k2][i], L2E, neg));
;       s[k2][i] = pv; ps += pv;
;     }
;   l = l * alpha + ps;
;   if (__builtin_amdgcn_ballot_w64(mn != m) != 0ull) {
; #pragma unroll
;     for (int dt = 0; dt < 2; ++dt)
; #pragma unroll
;       for (int i = 0; i < 16; ++i) o[dt][i] *= alpha;
;   }
;   m = mn;
; #pragma unroll
;   for (int st = 0; st < 4; ++st) {
;     if (!(HM & (1 << (st >> 1)))) continue;
;     const int k2 = st >> 1, b8 = 8 * (st & 1);
;     const u32x4 pw = {pack2(s[k2][b8], s[k2][b8 + 1]), pack2(s[k2][b8 + 2], s[k2][b8 + 3]), pack2(s[k2][b8 + 4], s[k2][b8 + 5]), pack2(s[k2][b8 + 6], s[k2][b8 + 7])};
;     const bf16x8 pb = __builtin_bit_cast(bf16x8, pw);
; #pragma unroll
;     for (int dt = 0; dt < 2; ++dt) {
;       const s16x4 lo = *(const s16x4*)(Vs + (32 * dt + r) * LSTR + 16 * st + 4 * h);
;       const s16x4 hi = *(const s16x4*)(Vs + (32 * dt + r) * LSTR + 16 * st + 8 + 4 * h);
;       const bf16x8 a = __builtin_shufflevector(lo, hi, 0, 1, 2, 3, 4, 5, 6, 7);
;       o[dt] = mfma32(a, pb, o[dt]);
;     }
;   }
.LBB0_712:
	v_fma_f32 v34, v34, s34, -v157
	v_exp_f32_e32 v46, v34
	v_fma_f32 v34, v35, s34, -v157
	v_exp_f32_e32 v47, v34
	v_fma_f32 v34, v36, s34, -v157
	v_exp_f32_e32 v48, v34
	v_fma_f32 v34, v37, s34, -v157
	v_add_f32_e32 v35, 0, v46
	v_exp_f32_e32 v49, v34
	v_fma_f32 v34, v38, s34, -v157
	v_add_f32_e32 v35, v47, v35
	v_exp_f32_e32 v38, v34
	v_fma_f32 v34, v39, s34, -v157
	v_exp_f32_e32 v39, v34
	v_add_f32_e32 v34, v48, v35
	v_fma_f32 v35, v50, s34, -v157
	v_exp_f32_e32 v50, v35
	v_fma_f32 v35, v51, s34, -v157
	v_add_f32_e32 v34, v49, v34
	v_exp_f32_e32 v51, v35
	v_fma_f32 v35, v52, s34, -v157
	v_add_f32_e32 v34, v38, v34
	v_exp_f32_e32 v52, v35
	v_fma_f32 v35, v53, s34, -v157
	v_add_f32_e32 v34, v39, v34
	v_exp_f32_e32 v53, v35
	v_add_f32_e32 v34, v50, v34
	v_add_f32_e32 v34, v51, v34
	v_add_f32_e32 v34, v52, v34
	v_add_f32_e32 v54, v53, v34
	v_fma_f32 v34, v44, s34, -v157
	v_fma_f32 v44, v45, s34, -v157
	v_add_u32_e32 v56, 0x6800, v198
	v_exp_f32_e32 v55, v34
	ds_read2_b64 v[34:37], v56 offset0:128 offset1:130
	v_exp_f32_e32 v57, v44
	v_cvt_pk_bf16_f32 v44, v46, v47
	v_cvt_pk_bf16_f32 v46, v38, v39
	v_add_u32_e32 v38, v199, v200
	v_add_u32_e32 v38, 0x7800, v38
	v_cvt_pk_bf16_f32 v45, v48, v49
	v_cvt_pk_bf16_f32 v47, v50, v51
	ds_read2_b64 v[48:51], v38 offset0:192 offset1:194
	v_fma_f32 v39, v40, s34, -v157
	s_waitcnt lgkmcnt(1)
	v_mfma_f32_32x32x16_bf16 v[2:17], v[34:37], v[44:47], v[2:17]
	v_fma_f32 v34, v41, s34, -v157
	v_exp_f32_e32 v58, v34
	v_fma_f32 v34, v42, s34, -v157
	v_exp_f32_e32 v59, v34
	v_fma_f32 v34, v43, s34, -v157
	v_exp_f32_e32 v60, v34
	ds_read2_b64 v[34:37], v56 offset0:132 offset1:134
	s_waitcnt lgkmcnt(1)
	v_mfma_f32_32x32x16_bf16 v[18:33], v[48:51], v[44:47], v[18:33]
	v_exp_f32_e32 v46, v39
	ds_read2_b64 v[38:41], v38 offset0:196 offset1:198
	v_cvt_pk_bf16_f32 v42, v52, v53
	v_cvt_pk_bf16_f32 v43, v55, v57
	v_cvt_pk_bf16_f32 v44, v58, v59
	v_cvt_pk_bf16_f32 v45, v60, v46
	s_waitcnt lgkmcnt(0)
	s_nop 0
	v_mfma_f32_32x32x16_bf16 v[18:33], v[38:41], v[42:45], v[18:33]
	v_mfma_f32_32x32x16_bf16 v[2:17], v[34:37], v[42:45], v[2:17]
	v_add_f32_e32 v34, v55, v54
	v_add_f32_e32 v34, v57, v34
	v_add_f32_e32 v34, v58, v34
	v_add_f32_e32 v34, v59, v34
	v_add_f32_e32 v34, v60, v34
	v_add_f32_e32 v159, v46, v34
	s_nop 4
	v_fmac_f32_e32 v159, v160, v0
.LBB0_713:
	s_branch .LBB0_715
.LBB0_714:
	v_mov_b32_e32 v159, v160
	v_mov_b32_e32 v157, v158

; DI unsigned pack2(float a, float b) { f32x2 v = {a, b}; bf16x2_t r = __builtin_convertvector(v, bf16x2_t); return __builtin_bit_cast(unsigned, r); }
; DI f32x16 mfma32(bf16x8 a, bf16x8 b, f32x16 c) { return __builtin_amdgcn_mfma_f32_32x32x16_bf16(a, b, c, 0, 0, 0); }
;     ...
;   const float mn = fmaxf(m, mx); const float alpha = __builtin_amdgcn_exp2f(m - mn);
;   const float neg = (MODE == 2 && !lanesel) ? NINF : -mn;
;   float ps = 0.f;
; #pragma unroll
;   for (int k2 = 0; k2 < 2; ++k2)
; #pragma unroll
;     for (int i = 0; i < 16; ++i) {
;       if (!(HM & (1 << k2))) continue;
;       const float pv = (MODE == 1) ? __builtin_amdgcn_exp2f(s[k2][i] + neg) : __builtin_amdgcn_exp2f(fmaf(s[k2][i], L2E, neg));
;       s[k2][i] = pv; ps += pv;
;     }
;   l = l * alpha + ps;
;   if (__builtin_amdgcn_ballot_w64(mn != m) != 0ull) {
; #pragma unroll
;     for (int dt = 0; dt < 2; ++dt)
; #pragma unroll
;       for (int i = 0; i < 16; ++i) o[dt][i] *= alpha;
;   }
;   m = mn;
; #pragma unroll
;   for (int st = 0; st < 4; ++st) {
;     if (!(HM & (1 << (st >> 1)))) continue;
;     const int k2 = st >> 1, b8 = 8 * (st & 1);
;     const u32x4 pw = {pack2(s[k2][b8], s[k2][b8 + 1]), pack2(s[k2][b8 + 2], s[k2][b8 + 3]), pack2(s[k2][b8 + 4], s[k2][b8 + 5]), pack2(s[k2][b8 + 6], s[k2][b8 + 7])};
;     const bf16x8 pb = __builtin_bit_cast(bf16x8, pw);
; #pragma unroll
;     for (int dt = 0; dt < 2; ++dt) {
;       const s16x4 lo = *(const s16x4*)(Vs + (32 * dt + r) * LSTR + 16 * st + 4 * h);
;       const s16x4 hi = *(const s16x4*)(Vs + (32 * dt + r) * LSTR + 16 * st + 8 + 4 * h);
;       const bf16x8 a = __builtin_shufflevector(lo, hi, 0, 1, 2, 3, 4, 5, 6, 7);
;       o[dt] = mfma32(a, pb, o[dt]);
;     }
;   }
.LBB0_792:
	v_sub_f32_e32 v65, v65, v192
	v_exp_f32_e32 v65, v65
	v_sub_f32_e32 v64, v64, v192
	v_exp_f32_e32 v64, v64
	v_sub_f32_e32 v63, v63, v192
	v_exp_f32_e32 v63, v63
	v_sub_f32_e32 v62, v62, v192
	v_exp_f32_e32 v62, v62
	v_sub_f32_e32 v61, v61, v192
	v_add_f32_e32 v114, 0, v65
	v_exp_f32_e32 v61, v61
	v_sub_f32_e32 v60, v60, v192
	v_add_f32_e32 v114, v64, v114
	v_exp_f32_e32 v60, v60
	v_sub_f32_e32 v59, v59, v192
	v_add_f32_e32 v114, v63, v114
	v_exp_f32_e32 v59, v59
	v_sub_f32_e32 v58, v58, v192
	v_add_f32_e32 v114, v62, v114
	v_exp_f32_e32 v58, v58
	v_sub_f32_e32 v57, v57, v192
	v_add_f32_e32 v114, v61, v114
	v_exp_f32_e32 v57, v57
	v_sub_f32_e32 v56, v56, v192
	v_add_f32_e32 v114, v60, v114
	v_exp_f32_e32 v56, v56
	v_sub_f32_e32 v55, v55, v192
	v_add_f32_e32 v114, v59, v114
	v_exp_f32_e32 v55, v55
	v_sub_f32_e32 v54, v54, v192
	v_add_f32_e32 v114, v58, v114
	v_exp_f32_e32 v54, v54
	v_sub_f32_e32 v53, v53, v192
	v_add_f32_e32 v114, v57, v114
	v_exp_f32_e32 v53, v53
	v_sub_f32_e32 v52, v52, v192
	v_add_f32_e32 v114, v56, v114
	v_exp_f32_e32 v52, v52
	v_sub_f32_e32 v51, v51, v192
	v_add_f32_e32 v114, v55, v114
	v_exp_f32_e32 v51, v51
	v_sub_f32_e32 v50, v50, v192
	v_add_f32_e32 v114, v54, v114
	v_exp_f32_e32 v50, v50
	v_sub_f32_e32 v49, v49, v192
	v_add_f32_e32 v114, v53, v114
	v_exp_f32_e32 v49, v49
	v_sub_f32_e32 v48, v48, v192
	v_add_f32_e32 v114, v52, v114
	v_exp_f32_e32 v48, v48
	v_sub_f32_e32 v47, v47, v192
	v_add_f32_e32 v114, v51, v114
	v_exp_f32_e32 v47, v47
	v_sub_f32_e32 v46, v46, v192
	v_add_f32_e32 v114, v50, v114
	v_exp_f32_e32 v46, v46
	v_sub_f32_e32 v41, v41, v192
	v_add_f32_e32 v114, v49, v114
	v_exp_f32_e32 v115, v41
	v_add_f32_e32 v114, v48, v114
	v_add_f32_e32 v114, v47, v114
	v_add_f32_e32 v114, v46, v114
	v_sub_f32_e32 v34, v34, v192
	v_add_f32_e32 v41, v115, v114
	v_exp_f32_e32 v114, v34
	v_sub_f32_e32 v35, v35, v192
	v_exp_f32_e32 v116, v35
	v_sub_f32_e32 v35, v36, v192
	v_exp_f32_e32 v117, v35
	v_sub_f32_e32 v35, v37, v192
	v_exp_f32_e32 v118, v35
	v_sub_f32_e32 v35, v38, v192
	v_add_f32_e32 v34, v114, v41
	v_exp_f32_e32 v119, v35
	v_sub_f32_e32 v35, v39, v192
	v_add_f32_e32 v34, v116, v34
	v_exp_f32_e32 v120, v35
	v_sub_f32_e32 v35, v40, v192
	v_add_f32_e32 v34, v117, v34
	v_exp_f32_e32 v121, v35
	v_sub_f32_e32 v35, v42, v192
	v_add_f32_e32 v34, v118, v34
	v_exp_f32_e32 v122, v35
	v_sub_f32_e32 v35, v43, v192
	v_add_f32_e32 v34, v119, v34
	v_exp_f32_e32 v123, v35
	v_sub_f32_e32 v35, v44, v192
	v_add_f32_e32 v34, v120, v34
	v_exp_f32_e32 v124, v35
	v_sub_f32_e32 v35, v45, v192
	v_add_f32_e32 v34, v121, v34
	v_exp_f32_e32 v125, v35
	v_add_f32_e32 v34, v122, v34
	v_add_f32_e32 v34, v123, v34
	v_add_f32_e32 v34, v124, v34
	v_add_f32_e32 v194, v125, v34
	v_fmac_f32_e32 v194, v193, v0
	v_add_u32_e32 v0, 0x2000, v198
	ds_read2_b64 v[38:41], v0 offset0:128 offset1:130
	ds_read2_b64 v[42:45], v0 offset0:132 offset1:134
	v_cvt_pk_bf16_f32 v34, v65, v64
	v_cvt_pk_bf16_f32 v35, v63, v62
	v_cvt_pk_bf16_f32 v36, v61, v60
	v_cvt_pk_bf16_f32 v37, v59, v58
	v_add_u32_e32 v58, 0x3000, v198
	s_waitcnt lgkmcnt(1)
	v_mfma_f32_32x32x16_bf16 v[2:17], v[38:41], v[34:37], v[2:17]
	ds_read2_b64 v[38:41], v58 offset0:192 offset1:194
	s_waitcnt lgkmcnt(0)
	v_mfma_f32_32x32x16_bf16 v[18:33], v[38:41], v[34:37], v[18:33]
	ds_read2_b64 v[38:41], v58 offset0:196 offset1:198
	v_cvt_pk_bf16_f32 v34, v57, v56
	v_cvt_pk_bf16_f32 v35, v55, v54
	v_cvt_pk_bf16_f32 v36, v53, v52
	v_cvt_pk_bf16_f32 v37, v51, v50
	s_waitcnt lgkmcnt(0)
	s_nop 0
	v_mfma_f32_32x32x16_bf16 v[18:33], v[38:41], v[34:37], v[18:33]
	ds_read2_b64 v[38:41], v0 offset0:136 offset1:138
	v_mfma_f32_32x32x16_bf16 v[2:17], v[42:45], v[34:37], v[2:17]
	v_cvt_pk_bf16_f32 v34, v49, v48
	v_cvt_pk_bf16_f32 v35, v47, v46
	v_cvt_pk_bf16_f32 v36, v115, v114
	v_cvt_pk_bf16_f32 v37, v116, v117
	s_waitcnt lgkmcnt(0)
	s_nop 0
	v_mfma_f32_32x32x16_bf16 v[2:17], v[38:41], v[34:37], v[2:17]
	ds_read2_b64 v[38:41], v58 offset0:200 offset1:202
	s_waitcnt lgkmcnt(0)
	v_mfma_f32_32x32x16_bf16 v[18:33], v[38:41], v[34:37], v[18:33]
	ds_read2_b64 v[38:41], v0 offset0:140 offset1:142
	v_cvt_pk_bf16_f32 v34, v118, v119
	v_cvt_pk_bf16_f32 v35, v120, v121
	v_cvt_pk_bf16_f32 v36, v122, v123
	v_cvt_pk_bf16_f32 v37, v124, v125
	s_waitcnt lgkmcnt(0)
	s_nop 0
	v_mfma_f32_32x32x16_bf16 v[2:17], v[38:41], v[34:37], v[2:17]
	ds_read2_b64 v[38:41], v58 offset0:204 offset1:206
	s_waitcnt lgkmcnt(0)
	v_mfma_f32_32x32x16_bf16 v[18:33], v[38:41], v[34:37], v[18:33]
	s_nop 8
.LBB0_793:
	s_branch .LBB0_795
.LBB0_794:
	v_mov_b32_e32 v194, v193
	v_mov_b32_e32 v192, v191

; DI unsigned pack2(float a, float b) { f32x2 v = {a, b}; bf16x2_t r = __builtin_convertvector(v, bf16x2_t); return __builtin_bit_cast(unsigned, r); }
; DI f32x16 mfma32(bf16x8 a, bf16x8 b, f32x16 c) { return __builtin_amdgcn_mfma_f32_32x32x16_bf16(a, b, c, 0, 0, 0); }
;     ...
;   const float mn = fmaxf(m, mx); const float alpha = __builtin_amdgcn_exp2f(m - mn);
;   const float neg = (MODE == 2 && !lanesel) ? NINF : -mn;
;   float ps = 0.f;
; #pragma unroll
;   for (int k2 = 0; k2 < 2; ++k2)
; #pragma unroll
;     for (int i = 0; i < 16; ++i) {
;       if (!(HM & (1 << k2))) continue;
;       const float pv = (MODE == 1) ? __builtin_amdgcn_exp2f(s[k2][i] + neg) : __builtin_amdgcn_exp2f(fmaf(s[k2][i], L2E, neg));
;       s[k2][i] = pv; ps += pv;
;     }
;   l = l * alpha + ps;
;   if (__builtin_amdgcn_ballot_w64(mn != m) != 0ull) {
; #pragma unroll
;     for (int dt = 0; dt < 2; ++dt)
; #pragma unroll
;       for (int i = 0; i < 16; ++i) o[dt][i] *= alpha;
;   }
;   m = mn;
; #pragma unroll
;   for (int st = 0; st < 4; ++st) {
;     if (!(HM & (1 << (st >> 1)))) continue;
;     const int k2 = st >> 1, b8 = 8 * (st & 1);
;     const u32x4 pw = {pack2(s[k2][b8], s[k2][b8 + 1]), pack2(s[k2][b8 + 2], s[k2][b8 + 3]), pack2(s[k2][b8 + 4], s[k2][b8 + 5]), pack2(s[k2][b8 + 6], s[k2][b8 + 7])};
;     const bf16x8 pb = __builtin_bit_cast(bf16x8, pw);
; #pragma unroll
;     for (int dt = 0; dt < 2; ++dt) {
;       const s16x4 lo = *(const s16x4*)(Vs + (32 * dt + r) * LSTR + 16 * st + 4 * h);
;       const s16x4 hi = *(const s16x4*)(Vs + (32 * dt + r) * LSTR + 16 * st + 8 + 4 * h);
;       const bf16x8 a = __builtin_shufflevector(lo, hi, 0, 1, 2, 3, 4, 5, 6, 7);
;       o[dt] = mfma32(a, pb, o[dt]);
;     }
;   }
.LBB0_806:
	v_sub_f32_e32 v65, v65, v191
	v_exp_f32_e32 v65, v65
	v_sub_f32_e32 v64, v64, v191
	v_exp_f32_e32 v64, v64
	v_sub_f32_e32 v63, v63, v191
	v_exp_f32_e32 v63, v63
	v_sub_f32_e32 v62, v62, v191
	v_exp_f32_e32 v62, v62
	v_sub_f32_e32 v61, v61, v191
	v_add_f32_e32 v114, 0, v65
	v_exp_f32_e32 v61, v61
	v_sub_f32_e32 v60, v60, v191
	v_add_f32_e32 v114, v64, v114
	v_exp_f32_e32 v60, v60
	v_sub_f32_e32 v59, v59, v191
	v_add_f32_e32 v114, v63, v114
	v_exp_f32_e32 v59, v59
	v_sub_f32_e32 v58, v58, v191
	v_add_f32_e32 v114, v62, v114
	v_exp_f32_e32 v58, v58
	v_sub_f32_e32 v57, v57, v191
	v_add_f32_e32 v114, v61, v114
	v_exp_f32_e32 v57, v57
	v_sub_f32_e32 v56, v56, v191
	v_add_f32_e32 v114, v60, v114
	v_exp_f32_e32 v56, v56
	v_sub_f32_e32 v55, v55, v191
	v_add_f32_e32 v114, v59, v114
	v_exp_f32_e32 v55, v55
	v_sub_f32_e32 v54, v54, v191
	v_add_f32_e32 v114, v58, v114
	v_exp_f32_e32 v54, v54
	v_sub_f32_e32 v53, v53, v191
	v_add_f32_e32 v114, v57, v114
	v_exp_f32_e32 v53, v53
	v_sub_f32_e32 v52, v52, v191
	v_add_f32_e32 v114, v56, v114
	v_exp_f32_e32 v52, v52
	v_sub_f32_e32 v51, v51, v191
	v_add_f32_e32 v114, v55, v114
	v_exp_f32_e32 v51, v51
	v_sub_f32_e32 v50, v50, v191
	v_add_f32_e32 v114, v54, v114
	v_exp_f32_e32 v50, v50
	v_sub_f32_e32 v49, v49, v191
	v_add_f32_e32 v114, v53, v114
	v_exp_f32_e32 v49, v49
	v_sub_f32_e32 v48, v48, v191
	v_add_f32_e32 v114, v52, v114
	v_exp_f32_e32 v48, v48
	v_sub_f32_e32 v47, v47, v191
	v_add_f32_e32 v114, v51, v114
	v_exp_f32_e32 v47, v47
	v_sub_f32_e32 v46, v46, v191
	v_add_f32_e32 v114, v50, v114
	v_exp_f32_e32 v46, v46
	v_sub_f32_e32 v41, v41, v191
	v_add_f32_e32 v114, v49, v114
	v_exp_f32_e32 v115, v41
	v_add_f32_e32 v114, v48, v114
	v_add_f32_e32 v114, v47, v114
	v_add_f32_e32 v114, v46, v114
	v_sub_f32_e32 v34, v34, v191
	v_add_f32_e32 v41, v115, v114
	v_exp_f32_e32 v114, v34
	v_sub_f32_e32 v35, v35, v191
	v_exp_f32_e32 v116, v35
	v_sub_f32_e32 v35, v36, v191
	v_exp_f32_e32 v117, v35
	v_sub_f32_e32 v35, v37, v191
	v_exp_f32_e32 v118, v35
	v_sub_f32_e32 v35, v38, v191
	v_add_f32_e32 v34, v114, v41
	v_exp_f32_e32 v119, v35
	v_sub_f32_e32 v35, v39, v191
	v_add_f32_e32 v34, v116, v34
	v_exp_f32_e32 v120, v35
	v_sub_f32_e32 v35, v40, v191
	v_add_f32_e32 v34, v117, v34
	v_exp_f32_e32 v121, v35
	v_sub_f32_e32 v35, v42, v191
	v_add_f32_e32 v34, v118, v34
	v_exp_f32_e32 v122, v35
	v_sub_f32_e32 v35, v43, v191
	v_add_f32_e32 v34, v119, v34
	v_exp_f32_e32 v123, v35
	v_sub_f32_e32 v35, v44, v191
	v_add_f32_e32 v34, v120, v34
	v_exp_f32_e32 v124, v35
	v_sub_f32_e32 v35, v45, v191
	v_add_f32_e32 v34, v121, v34
	v_exp_f32_e32 v125, v35
	v_add_f32_e32 v34, v122, v34
	v_add_f32_e32 v34, v123, v34
	v_add_f32_e32 v34, v124, v34
	v_add_f32_e32 v193, v125, v34
	v_fmac_f32_e32 v193, v194, v0
	v_add_u32_e32 v0, 0x6800, v198
	ds_read2_b64 v[38:41], v0 offset0:128 offset1:130
	ds_read2_b64 v[42:45], v0 offset0:132 offset1:134
	v_cvt_pk_bf16_f32 v34, v65, v64
	v_cvt_pk_bf16_f32 v35, v63, v62
	v_cvt_pk_bf16_f32 v36, v61, v60
	v_cvt_pk_bf16_f32 v37, v59, v58
	v_add_u32_e32 v58, 0x7800, v198
	s_waitcnt lgkmcnt(1)
	v_mfma_f32_32x32x16_bf16 v[2:17], v[38:41], v[34:37], v[2:17]
	ds_read2_b64 v[38:41], v58 offset0:192 offset1:194
	s_waitcnt lgkmcnt(0)
	v_mfma_f32_32x32x16_bf16 v[18:33], v[38:41], v[34:37], v[18:33]
	ds_read2_b64 v[38:41], v58 offset0:196 offset1:198
	v_cvt_pk_bf16_f32 v34, v57, v56
	v_cvt_pk_bf16_f32 v35, v55, v54
	v_cvt_pk_bf16_f32 v36, v53, v52
	v_cvt_pk_bf16_f32 v37, v51, v50
	s_waitcnt lgkmcnt(0)
	s_nop 0
	v_mfma_f32_32x32x16_bf16 v[18:33], v[38:41], v[34:37], v[18:33]
	ds_read2_b64 v[38:41], v0 offset0:136 offset1:138
	v_mfma_f32_32x32x16_bf16 v[2:17], v[42:45], v[34:37], v[2:17]
	v_cvt_pk_bf16_f32 v34, v49, v48
	v_cvt_pk_bf16_f32 v35, v47, v46
	v_cvt_pk_bf16_f32 v36, v115, v114
	v_cvt_pk_bf16_f32 v37, v116, v117
	s_waitcnt lgkmcnt(0)
	s_nop 0
	v_mfma_f32_32x32x16_bf16 v[2:17], v[38:41], v[34:37], v[2:17]
	ds_read2_b64 v[38:41], v58 offset0:200 offset1:202
	s_waitcnt lgkmcnt(0)
	v_mfma_f32_32x32x16_bf16 v[18:33], v[38:41], v[34:37], v[18:33]
	ds_read2_b64 v[38:41], v0 offset0:140 offset1:142
	v_cvt_pk_bf16_f32 v34, v118, v119
	v_cvt_pk_bf16_f32 v35, v120, v121
	v_cvt_pk_bf16_f32 v36, v122, v123
	v_cvt_pk_bf16_f32 v37, v124, v125
	s_waitcnt lgkmcnt(0)
	s_nop 0
	v_mfma_f32_32x32x16_bf16 v[2:17], v[38:41], v[34:37], v[2:17]
	ds_read2_b64 v[38:41], v58 offset0:204 offset1:206
	s_waitcnt lgkmcnt(0)
	v_mfma_f32_32x32x16_bf16 v[18:33], v[38:41], v[34:37], v[18:33]
	s_nop 8
.LBB0_807:
	s_branch .LBB0_809
.LBB0_808:
	v_mov_b32_e32 v193, v194
	v_mov_b32_e32 v191, v192

; template <int MODE>
; DI void flash_loop(char* smem, const bf16_t* Kbase, size_t ldk, const bf16_t* Vtbase, size_t ldv, ull tiles, ull wtiles,
;                    const bf16x8 (&qf)[4], f32x16 (&o)[2], float& m, float& l, int tq, int tqmin, int tqmax, int maxdist, const float* cn_lds, ull lmask) {
;     ...
;   while (true) {
;     stash(0, ka, va);
;     __syncthreads();
;     const int t2 = next_tile(); if (t2 >= 0) issue(t2, ka, va);
;     compute(t0, 0);
;     if (t1 < 0) break;
;     stash(1, kb, vb);
;     __syncthreads();
;     const int t3 = next_tile(); if (t3 >= 0) issue(t3, kb, vb);
;     compute(t1, 1);
;     if (t2 < 0) break;
;     t0 = t2; t1 = t3;
;   }
.LBB0_832:
	v_cmp_gt_i32_e32 vcc, 0, v215
	s_cbranch_vccnz .LBB0_820
	s_branch .LBB0_834

; DI unsigned pack2(float a, float b) { f32x2 v = {a, b}; bf16x2_t r = __builtin_convertvector(v, bf16x2_t); return __builtin_bit_cast(unsigned, r); }
; DI f32x16 mfma32(bf16x8 a, bf16x8 b, f32x16 c) { return __builtin_amdgcn_mfma_f32_32x32x16_bf16(a, b, c, 0, 0, 0); }
;     ...
;   const float mn = fmaxf(m, mx); const float alpha = __builtin_amdgcn_exp2f(m - mn);
;   const float neg = (MODE == 2 && !lanesel) ? NINF : -mn;
;   float ps = 0.f;
; #pragma unroll
;   for (int k2 = 0; k2 < 2; ++k2)
; #pragma unroll
;     for (int i = 0; i < 16; ++i) {
;       if (!(HM & (1 << k2))) continue;
;       const float pv = (MODE == 1) ? __builtin_amdgcn_exp2f(s[k2][i] + neg) : __builtin_amdgcn_exp2f(fmaf(s[k2][i], L2E, neg));
;       s[k2][i] = pv; ps += pv;
;     }
;   l = l * alpha + ps;
;   if (__builtin_amdgcn_ballot_w64(mn != m) != 0ull) {
; #pragma unroll
;     for (int dt = 0; dt < 2; ++dt)
; #pragma unroll
;       for (int i = 0; i < 16; ++i) o[dt][i] *= alpha;
;   }
;   m = mn;
; #pragma unroll
;   for (int st = 0; st < 4; ++st) {
;     if (!(HM & (1 << (st >> 1)))) continue;
;     const int k2 = st >> 1, b8 = 8 * (st & 1);
;     const u32x4 pw = {pack2(s[k2][b8], s[k2][b8 + 1]), pack2(s[k2][b8 + 2], s[k2][b8 + 3]), pack2(s[k2][b8 + 4], s[k2][b8 + 5]), pack2(s[k2][b8 + 6], s[k2][b8 + 7])};
;     const bf16x8 pb = __builtin_bit_cast(bf16x8, pw);
; #pragma unroll
;     for (int dt = 0; dt < 2; ++dt) {
;       const s16x4 lo = *(const s16x4*)(Vs + (32 * dt + r) * LSTR + 16 * st + 4 * h);
;       const s16x4 hi = *(const s16x4*)(Vs + (32 * dt + r) * LSTR + 16 * st + 8 + 4 * h);
;       const bf16x8 a = __builtin_shufflevector(lo, hi, 0, 1, 2, 3, 4, 5, 6, 7);
;       o[dt] = mfma32(a, pb, o[dt]);
;     }
;   }
.LBB0_844:
	v_cndmask_b32_e64 v45, -v211, v204, s[6:7]
	v_fmamk_f32 v46, v66, 0x3fb8aa3b, v45
	v_exp_f32_e32 v46, v46
	v_fmamk_f32 v48, v50, 0x3fb8aa3b, v45
	v_exp_f32_e32 v48, v48
	v_fmamk_f32 v49, v51, 0x3fb8aa3b, v45
	v_exp_f32_e32 v49, v49
	v_fmamk_f32 v50, v52, 0x3fb8aa3b, v45
	v_exp_f32_e32 v50, v50
	v_fmamk_f32 v51, v53, 0x3fb8aa3b, v45
	v_add_f32_e32 v47, 0, v46
	v_exp_f32_e32 v51, v51
	v_fmamk_f32 v52, v54, 0x3fb8aa3b, v45
	v_add_f32_e32 v47, v48, v47
	v_exp_f32_e32 v52, v52
	v_fmamk_f32 v53, v55, 0x3fb8aa3b, v45
	v_add_f32_e32 v47, v49, v47
	v_exp_f32_e32 v53, v53
	v_fmamk_f32 v54, v56, 0x3fb8aa3b, v45
	v_add_f32_e32 v47, v50, v47
	v_exp_f32_e32 v54, v54
	v_fmamk_f32 v55, v67, 0x3fb8aa3b, v45
	v_add_f32_e32 v47, v51, v47
	v_exp_f32_e32 v55, v55
	v_fmamk_f32 v56, v72, 0x3fb8aa3b, v45
	v_add_f32_e32 v47, v52, v47
	v_exp_f32_e32 v56, v56
	v_fmamk_f32 v64, v70, 0x3fb8aa3b, v45
	v_add_f32_e32 v47, v53, v47
	v_exp_f32_e32 v64, v64
	v_fmamk_f32 v65, v71, 0x3fb8aa3b, v45
	v_add_f32_e32 v47, v54, v47
	v_exp_f32_e32 v65, v65
	v_fmamk_f32 v66, v68, 0x3fb8aa3b, v45
	v_add_f32_e32 v47, v55, v47
	v_exp_f32_e32 v66, v66
	v_fmamk_f32 v67, v69, 0x3fb8aa3b, v45
	v_add_f32_e32 v47, v56, v47
	v_exp_f32_e32 v67, v67
	v_fmamk_f32 v62, v62, 0x3fb8aa3b, v45
	v_add_f32_e32 v47, v64, v47
	v_exp_f32_e32 v62, v62
	v_fmamk_f32 v63, v63, 0x3fb8aa3b, v45
	v_add_f32_e32 v47, v65, v47
	v_exp_f32_e32 v63, v63
	v_fmamk_f32 v61, v61, 0x3fb8aa3b, v45
	v_add_f32_e32 v47, v66, v47
	v_exp_f32_e32 v61, v61
	v_fmamk_f32 v60, v60, 0x3fb8aa3b, v45
	v_add_f32_e32 v47, v67, v47
	v_exp_f32_e32 v60, v60
	v_fmamk_f32 v59, v59, 0x3fb8aa3b, v45
	v_add_f32_e32 v47, v62, v47
	v_exp_f32_e32 v59, v59
	v_fmamk_f32 v58, v58, 0x3fb8aa3b, v45
	v_add_f32_e32 v47, v63, v47
	v_exp_f32_e32 v58, v58
	v_fmamk_f32 v57, v57, 0x3fb8aa3b, v45
	v_add_f32_e32 v47, v61, v47
	v_exp_f32_e32 v57, v57
	v_fmamk_f32 v34, v34, 0x3fb8aa3b, v45
	v_add_f32_e32 v47, v60, v47
	v_exp_f32_e32 v68, v34
	v_add_f32_e32 v47, v59, v47
	v_add_f32_e32 v47, v58, v47
	v_add_f32_e32 v47, v57, v47
	v_fmamk_f32 v35, v35, 0x3fb8aa3b, v45
	v_add_f32_e32 v34, v68, v47
	v_exp_f32_e32 v47, v35
	v_fmamk_f32 v35, v36, 0x3fb8aa3b, v45
	v_exp_f32_e32 v69, v35
	v_fmamk_f32 v35, v37, 0x3fb8aa3b, v45
	v_exp_f32_e32 v70, v35
	v_fmamk_f32 v35, v38, 0x3fb8aa3b, v45
	v_exp_f32_e32 v71, v35
	v_fmamk_f32 v35, v39, 0x3fb8aa3b, v45
	v_add_f32_e32 v34, v47, v34
	v_exp_f32_e32 v72, v35
	v_fmamk_f32 v35, v40, 0x3fb8aa3b, v45
	v_add_f32_e32 v34, v69, v34
	v_exp_f32_e32 v73, v35
	v_fmamk_f32 v35, v41, 0x3fb8aa3b, v45
	v_add_f32_e32 v34, v70, v34
	v_exp_f32_e32 v74, v35
	v_fmamk_f32 v35, v42, 0x3fb8aa3b, v45
	v_add_f32_e32 v34, v71, v34
	v_exp_f32_e32 v75, v35
	v_fmamk_f32 v35, v43, 0x3fb8aa3b, v45
	v_add_f32_e32 v34, v72, v34
	v_exp_f32_e32 v76, v35
	v_fmac_f32_e32 v45, 0x3fb8aa3b, v44
	v_add_f32_e32 v34, v73, v34
	v_exp_f32_e32 v77, v45
	v_add_f32_e32 v34, v74, v34
	v_add_f32_e32 v34, v75, v34
	v_add_f32_e32 v34, v76, v34
	v_add_f32_e32 v213, v77, v34
	v_fmac_f32_e32 v213, v214, v0
	v_add_u32_e32 v0, 0x6800, v198
	ds_read2_b64 v[38:41], v0 offset0:128 offset1:130
	ds_read2_b64 v[42:45], v0 offset0:132 offset1:134
	v_cvt_pk_bf16_f32 v34, v46, v48
	v_cvt_pk_bf16_f32 v35, v49, v50
	v_cvt_pk_bf16_f32 v36, v51, v52
	v_cvt_pk_bf16_f32 v37, v53, v54
	v_add_u32_e32 v46, 0x7800, v198
	s_waitcnt lgkmcnt(1)
	v_mfma_f32_32x32x16_bf16 v[2:17], v[38:41], v[34:37], v[2:17]
	ds_read2_b64 v[38:41], v46 offset0:192 offset1:194
	s_waitcnt lgkmcnt(0)
	v_mfma_f32_32x32x16_bf16 v[18:33], v[38:41], v[34:37], v[18:33]
	ds_read2_b64 v[38:41], v46 offset0:196 offset1:198
	v_cvt_pk_bf16_f32 v34, v55, v56
	v_cvt_pk_bf16_f32 v35, v64, v65
	v_cvt_pk_bf16_f32 v36, v66, v67
	v_cvt_pk_bf16_f32 v37, v62, v63
	s_waitcnt lgkmcnt(0)
	s_nop 0
	v_mfma_f32_32x32x16_bf16 v[18:33], v[38:41], v[34:37], v[18:33]
	ds_read2_b64 v[38:41], v0 offset0:136 offset1:138
	v_mfma_f32_32x32x16_bf16 v[2:17], v[42:45], v[34:37], v[2:17]
	v_cvt_pk_bf16_f32 v34, v61, v60
	v_cvt_pk_bf16_f32 v35, v59, v58
	v_cvt_pk_bf16_f32 v36, v57, v68
	v_cvt_pk_bf16_f32 v37, v47, v69
	s_waitcnt lgkmcnt(0)
	s_nop 0
	v_mfma_f32_32x32x16_bf16 v[2:17], v[38:41], v[34:37], v[2:17]
	ds_read2_b64 v[38:41], v46 offset0:200 offset1:202
	s_waitcnt lgkmcnt(0)
	v_mfma_f32_32x32x16_bf16 v[18:33], v[38:41], v[34:37], v[18:33]
	ds_read2_b64 v[38:41], v0 offset0:140 offset1:142
	v_cvt_pk_bf16_f32 v34, v70, v71
	v_cvt_pk_bf16_f32 v35, v72, v73
	v_cvt_pk_bf16_f32 v36, v74, v75
	v_cvt_pk_bf16_f32 v37, v76, v77
	s_waitcnt lgkmcnt(0)
	s_nop 0
	v_mfma_f32_32x32x16_bf16 v[2:17], v[38:41], v[34:37], v[2:17]
	ds_read2_b64 v[38:41], v46 offset0:204 offset1:206
	s_waitcnt lgkmcnt(0)
	v_mfma_f32_32x32x16_bf16 v[18:33], v[38:41], v[34:37], v[18:33]
	s_nop 8
.LBB0_845:
	s_branch .LBB0_847
.LBB0_846:
	v_mov_b32_e32 v213, v214
	v_mov_b32_e32 v211, v212

; DI unsigned pack2(float a, float b) { f32x2 v = {a, b}; bf16x2_t r = __builtin_convertvector(v, bf16x2_t); return __builtin_bit_cast(unsigned, r); }
; DI f32x16 mfma32(bf16x8 a, bf16x8 b, f32x16 c) { return __builtin_amdgcn_mfma_f32_32x32x16_bf16(a, b, c, 0, 0, 0); }
;     ...
;   const float mn = fmaxf(m, mx); const float alpha = __builtin_amdgcn_exp2f(m - mn);
;   const float neg = (MODE == 2 && !lanesel) ? NINF : -mn;
;   float ps = 0.f;
; #pragma unroll
;   for (int k2 = 0; k2 < 2; ++k2)
; #pragma unroll
;     for (int i = 0; i < 16; ++i) {
;       if (!(HM & (1 << k2))) continue;
;       const float pv = (MODE == 1) ? __builtin_amdgcn_exp2f(s[k2][i] + neg) : __builtin_amdgcn_exp2f(fmaf(s[k2][i], L2E, neg));
;       s[k2][i] = pv; ps += pv;
;     }
;   l = l * alpha + ps;
;   if (__builtin_amdgcn_ballot_w64(mn != m) != 0ull) {
; #pragma unroll
;     for (int dt = 0; dt < 2; ++dt)
; #pragma unroll
;       for (int i = 0; i < 16; ++i) o[dt][i] *= alpha;
;   }
;   m = mn;
; #pragma unroll
;   for (int st = 0; st < 4; ++st) {
;     if (!(HM & (1 << (st >> 1)))) continue;
;     const int k2 = st >> 1, b8 = 8 * (st & 1);
;     const u32x4 pw = {pack2(s[k2][b8], s[k2][b8 + 1]), pack2(s[k2][b8 + 2], s[k2][b8 + 3]), pack2(s[k2][b8 + 4], s[k2][b8 + 5]), pack2(s[k2][b8 + 6], s[k2][b8 + 7])};
;     const bf16x8 pb = __builtin_bit_cast(bf16x8, pw);
; #pragma unroll
;     for (int dt = 0; dt < 2; ++dt) {
;       const s16x4 lo = *(const s16x4*)(Vs + (32 * dt + r) * LSTR + 16 * st + 4 * h);
;       const s16x4 hi = *(const s16x4*)(Vs + (32 * dt + r) * LSTR + 16 * st + 8 + 4 * h);
;       const bf16x8 a = __builtin_shufflevector(lo, hi, 0, 1, 2, 3, 4, 5, 6, 7);
;       o[dt] = mfma32(a, pb, o[dt]);
;     }
;   }
.LBB0_945:
	v_fma_f32 v34, v34, s34, -v160
	v_exp_f32_e32 v45, v34
	v_fma_f32 v34, v35, s34, -v160
	v_exp_f32_e32 v46, v34
	v_fma_f32 v34, v36, s34, -v160
	v_exp_f32_e32 v47, v34
	v_fma_f32 v34, v37, s34, -v160
	v_add_f32_e32 v35, 0, v45
	v_exp_f32_e32 v48, v34
	v_fma_f32 v34, v38, s34, -v160
	v_add_f32_e32 v35, v46, v35
	v_exp_f32_e32 v38, v34
	v_fma_f32 v34, v39, s34, -v160
	v_exp_f32_e32 v39, v34
	v_add_f32_e32 v34, v47, v35
	v_fma_f32 v35, v50, s34, -v160
	v_exp_f32_e32 v49, v35
	v_fma_f32 v35, v51, s34, -v160
	v_add_f32_e32 v34, v48, v34
	v_exp_f32_e32 v50, v35
	v_fma_f32 v35, v52, s34, -v160
	v_add_f32_e32 v34, v38, v34
	v_exp_f32_e32 v52, v35
	v_fma_f32 v35, v53, s34, -v160
	v_add_f32_e32 v34, v39, v34
	v_exp_f32_e32 v53, v35
	v_add_f32_e32 v34, v49, v34
	v_add_f32_e32 v34, v50, v34
	v_add_f32_e32 v34, v52, v34
	v_add_f32_e32 v55, v53, v34
	v_fma_f32 v34, v54, s34, -v160
	v_add_u32_e32 v56, 0x2000, v198
	v_exp_f32_e32 v54, v34
	ds_read2_b64 v[34:37], v56 offset0:128 offset1:130
	v_fma_f32 v44, v44, s34, -v160
	v_exp_f32_e32 v57, v44
	v_cvt_pk_bf16_f32 v44, v45, v46
	v_cvt_pk_bf16_f32 v46, v38, v39
	v_add_u32_e32 v38, 0x3000, v198
	v_cvt_pk_bf16_f32 v45, v47, v48
	v_cvt_pk_bf16_f32 v47, v49, v50
	ds_read2_b64 v[48:51], v38 offset0:192 offset1:194
	v_fma_f32 v39, v40, s34, -v160
	s_waitcnt lgkmcnt(1)
	v_mfma_f32_32x32x16_bf16 v[2:17], v[34:37], v[44:47], v[2:17]
	v_fma_f32 v34, v41, s34, -v160
	v_exp_f32_e32 v58, v34
	v_fma_f32 v34, v42, s34, -v160
	v_exp_f32_e32 v59, v34
	v_fma_f32 v34, v43, s34, -v160
	v_exp_f32_e32 v60, v34
	ds_read2_b64 v[34:37], v56 offset0:132 offset1:134
	s_waitcnt lgkmcnt(1)
	v_mfma_f32_32x32x16_bf16 v[18:33], v[48:51], v[44:47], v[18:33]
	v_exp_f32_e32 v46, v39
	ds_read2_b64 v[38:41], v38 offset0:196 offset1:198
	v_cvt_pk_bf16_f32 v42, v52, v53
	v_cvt_pk_bf16_f32 v43, v54, v57
	v_cvt_pk_bf16_f32 v44, v58, v59
	v_cvt_pk_bf16_f32 v45, v60, v46
	s_waitcnt lgkmcnt(0)
	s_nop 0
	v_mfma_f32_32x32x16_bf16 v[18:33], v[38:41], v[42:45], v[18:33]
	v_mfma_f32_32x32x16_bf16 v[2:17], v[34:37], v[42:45], v[2:17]
	v_add_f32_e32 v34, v54, v55
	v_add_f32_e32 v34, v57, v34
	v_add_f32_e32 v34, v58, v34
	v_add_f32_e32 v34, v59, v34
	v_add_f32_e32 v34, v60, v34
	v_add_f32_e32 v162, v46, v34
	s_nop 4
	v_fmac_f32_e32 v162, v161, v0
.LBB0_946:
	s_branch .LBB0_948
.LBB0_947:
	v_mov_b32_e32 v162, v161
	v_mov_b32_e32 v160, v159

; DI unsigned pack2(float a, float b) { f32x2 v = {a, b}; bf16x2_t r = __builtin_convertvector(v, bf16x2_t); return __builtin_bit_cast(unsigned, r); }
; DI f32x16 mfma32(bf16x8 a, bf16x8 b, f32x16 c) { return __builtin_amdgcn_mfma_f32_32x32x16_bf16(a, b, c, 0, 0, 0); }
;     ...
;   const float mn = fmaxf(m, mx); const float alpha = __builtin_amdgcn_exp2f(m - mn);
;   const float neg = (MODE == 2 && !lanesel) ? NINF : -mn;
;   float ps = 0.f;
; #pragma unroll
;   for (int k2 = 0; k2 < 2; ++k2)
; #pragma unroll
;     for (int i = 0; i < 16; ++i) {
;       if (!(HM & (1 << k2))) continue;
;       const float pv = (MODE == 1) ? __builtin_amdgcn_exp2f(s[k2][i] + neg) : __builtin_amdgcn_exp2f(fmaf(s[k2][i], L2E, neg));
;       s[k2][i] = pv; ps += pv;
;     }
;   l = l * alpha + ps;
;   if (__builtin_amdgcn_ballot_w64(mn != m) != 0ull) {
; #pragma unroll
;     for (int dt = 0; dt < 2; ++dt)
; #pragma unroll
;       for (int i = 0; i < 16; ++i) o[dt][i] *= alpha;
;   }
;   m = mn;
; #pragma unroll
;   for (int st = 0; st < 4; ++st) {
;     if (!(HM & (1 << (st >> 1)))) continue;
;     const int k2 = st >> 1, b8 = 8 * (st & 1);
;     const u32x4 pw = {pack2(s[k2][b8], s[k2][b8 + 1]), pack2(s[k2][b8 + 2], s[k2][b8 + 3]), pack2(s[k2][b8 + 4], s[k2][b8 + 5]), pack2(s[k2][b8 + 6], s[k2][b8 + 7])};
;     const bf16x8 pb = __builtin_bit_cast(bf16x8, pw);
; #pragma unroll
;     for (int dt = 0; dt < 2; ++dt) {
;       const s16x4 lo = *(const s16x4*)(Vs + (32 * dt + r) * LSTR + 16 * st + 4 * h);
;       const s16x4 hi = *(const s16x4*)(Vs + (32 * dt + r) * LSTR + 16 * st + 8 + 4 * h);
;       const bf16x8 a = __builtin_shufflevector(lo, hi, 0, 1, 2, 3, 4, 5, 6, 7);
;       o[dt] = mfma32(a, pb, o[dt]);
;     }
;   }
.LBB0_973:
	v_fma_f32 v34, v34, s34, -v159
	v_exp_f32_e32 v46, v34
	v_fma_f32 v34, v35, s34, -v159
	v_exp_f32_e32 v47, v34
	v_fma_f32 v34, v36, s34, -v159
	v_exp_f32_e32 v48, v34
	v_fma_f32 v34, v37, s34, -v159
	v_add_f32_e32 v35, 0, v46
	v_exp_f32_e32 v49, v34
	v_fma_f32 v34, v38, s34, -v159
	v_add_f32_e32 v35, v47, v35
	v_exp_f32_e32 v38, v34
	v_fma_f32 v34, v39, s34, -v159
	v_exp_f32_e32 v39, v34
	v_add_f32_e32 v34, v48, v35
	v_fma_f32 v35, v50, s34, -v159
	v_exp_f32_e32 v50, v35
	v_fma_f32 v35, v51, s34, -v159
	v_add_f32_e32 v34, v49, v34
	v_exp_f32_e32 v51, v35
	v_fma_f32 v35, v52, s34, -v159
	v_add_f32_e32 v34, v38, v34
	v_exp_f32_e32 v52, v35
	v_fma_f32 v35, v53, s34, -v159
	v_add_f32_e32 v34, v39, v34
	v_exp_f32_e32 v53, v35
	v_add_f32_e32 v34, v50, v34
	v_add_f32_e32 v34, v51, v34
	v_add_f32_e32 v34, v52, v34
	v_add_f32_e32 v54, v53, v34
	v_fma_f32 v34, v44, s34, -v159
	v_fma_f32 v44, v45, s34, -v159
	v_add_u32_e32 v56, 0x6800, v198
	v_exp_f32_e32 v55, v34
	ds_read2_b64 v[34:37], v56 offset0:128 offset1:130
	v_exp_f32_e32 v57, v44
	v_cvt_pk_bf16_f32 v44, v46, v47
	v_cvt_pk_bf16_f32 v46, v38, v39
	v_add_u32_e32 v38, v199, v200
	v_add_u32_e32 v38, 0x7800, v38
	v_cvt_pk_bf16_f32 v45, v48, v49
	v_cvt_pk_bf16_f32 v47, v50, v51
	ds_read2_b64 v[48:51], v38 offset0:192 offset1:194
	v_fma_f32 v39, v40, s34, -v159
	s_waitcnt lgkmcnt(1)
	v_mfma_f32_32x32x16_bf16 v[2:17], v[34:37], v[44:47], v[2:17]
	v_fma_f32 v34, v41, s34, -v159
	v_exp_f32_e32 v58, v34
	v_fma_f32 v34, v42, s34, -v159
	v_exp_f32_e32 v59, v34
	v_fma_f32 v34, v43, s34, -v159
	v_exp_f32_e32 v60, v34
	ds_read2_b64 v[34:37], v56 offset0:132 offset1:134
	s_waitcnt lgkmcnt(1)
	v_mfma_f32_32x32x16_bf16 v[18:33], v[48:51], v[44:47], v[18:33]
	v_exp_f32_e32 v46, v39
	ds_read2_b64 v[38:41], v38 offset0:196 offset1:198
	v_cvt_pk_bf16_f32 v42, v52, v53
	v_cvt_pk_bf16_f32 v43, v55, v57
	v_cvt_pk_bf16_f32 v44, v58, v59
	v_cvt_pk_bf16_f32 v45, v60, v46
	s_waitcnt lgkmcnt(0)
	s_nop 0
	v_mfma_f32_32x32x16_bf16 v[18:33], v[38:41], v[42:45], v[18:33]
	v_mfma_f32_32x32x16_bf16 v[2:17], v[34:37], v[42:45], v[2:17]
	v_add_f32_e32 v34, v55, v54
	v_add_f32_e32 v34, v57, v34
	v_add_f32_e32 v34, v58, v34
	v_add_f32_e32 v34, v59, v34
	v_add_f32_e32 v34, v60, v34
	v_add_f32_e32 v161, v46, v34
	s_nop 4
	v_fmac_f32_e32 v161, v162, v0
.LBB0_974:
	s_branch .LBB0_976
.LBB0_975:
	v_mov_b32_e32 v161, v162
	v_mov_b32_e32 v159, v160

; DI unsigned pack2(float a, float b) { f32x2 v = {a, b}; bf16x2_t r = __builtin_convertvector(v, bf16x2_t); return __builtin_bit_cast(unsigned, r); }
; DI f32x16 mfma32(bf16x8 a, bf16x8 b, f32x16 c) { return __builtin_amdgcn_mfma_f32_32x32x16_bf16(a, b, c, 0, 0, 0); }
;     ...
;   const float mn = fmaxf(m, mx); const float alpha = __builtin_amdgcn_exp2f(m - mn);
;   const float neg = (MODE == 2 && !lanesel) ? NINF : -mn;
;   float ps = 0.f;
; #pragma unroll
;   for (int k2 = 0; k2 < 2; ++k2)
; #pragma unroll
;     for (int i = 0; i < 16; ++i) {
;       if (!(HM & (1 << k2))) continue;
;       const float pv = (MODE == 1) ? __builtin_amdgcn_exp2f(s[k2][i] + neg) : __builtin_amdgcn_exp2f(fmaf(s[k2][i], L2E, neg));
;       s[k2][i] = pv; ps += pv;
;     }
;   l = l * alpha + ps;
;   if (__builtin_amdgcn_ballot_w64(mn != m) != 0ull) {
; #pragma unroll
;     for (int dt = 0; dt < 2; ++dt)
; #pragma unroll
;       for (int i = 0; i < 16; ++i) o[dt][i] *= alpha;
;   }
;   m = mn;
; #pragma unroll
;   for (int st = 0; st < 4; ++st) {
;     if (!(HM & (1 << (st >> 1)))) continue;
;     const int k2 = st >> 1, b8 = 8 * (st & 1);
;     const u32x4 pw = {pack2(s[k2][b8], s[k2][b8 + 1]), pack2(s[k2][b8 + 2], s[k2][b8 + 3]), pack2(s[k2][b8 + 4], s[k2][b8 + 5]), pack2(s[k2][b8 + 6], s[k2][b8 + 7])};
;     const bf16x8 pb = __builtin_bit_cast(bf16x8, pw);
; #pragma unroll
;     for (int dt = 0; dt < 2; ++dt) {
;       const s16x4 lo = *(const s16x4*)(Vs + (32 * dt + r) * LSTR + 16 * st + 4 * h);
;       const s16x4 hi = *(const s16x4*)(Vs + (32 * dt + r) * LSTR + 16 * st + 8 + 4 * h);
;       const bf16x8 a = __builtin_shufflevector(lo, hi, 0, 1, 2, 3, 4, 5, 6, 7);
;       o[dt] = mfma32(a, pb, o[dt]);
;     }
;   }
.LBB0_1012:
	v_fma_f32 v34, v34, s34, -v158
	v_exp_f32_e32 v45, v34
	v_fma_f32 v34, v35, s34, -v158
	v_exp_f32_e32 v46, v34
	v_fma_f32 v34, v36, s34, -v158
	v_exp_f32_e32 v47, v34
	v_fma_f32 v34, v37, s34, -v158
	v_add_f32_e32 v35, 0, v45
	v_exp_f32_e32 v48, v34
	v_fma_f32 v34, v38, s34, -v158
	v_add_f32_e32 v35, v46, v35
	v_exp_f32_e32 v38, v34
	v_fma_f32 v34, v39, s34, -v158
	v_exp_f32_e32 v39, v34
	v_add_f32_e32 v34, v47, v35
	v_fma_f32 v35, v50, s34, -v158
	v_exp_f32_e32 v49, v35
	v_fma_f32 v35, v51, s34, -v158
	v_add_f32_e32 v34, v48, v34
	v_exp_f32_e32 v50, v35
	v_fma_f32 v35, v52, s34, -v158
	v_add_f32_e32 v34, v38, v34
	v_exp_f32_e32 v52, v35
	v_fma_f32 v35, v53, s34, -v158
	v_add_f32_e32 v34, v39, v34
	v_exp_f32_e32 v53, v35
	v_add_f32_e32 v34, v49, v34
	v_add_f32_e32 v34, v50, v34
	v_add_f32_e32 v34, v52, v34
	v_add_f32_e32 v55, v53, v34
	v_fma_f32 v34, v54, s34, -v158
	v_add_u32_e32 v56, 0x2000, v198
	v_exp_f32_e32 v54, v34
	ds_read2_b64 v[34:37], v56 offset0:128 offset1:130
	v_fma_f32 v44, v44, s34, -v158
	v_exp_f32_e32 v57, v44
	v_cvt_pk_bf16_f32 v44, v45, v46
	v_cvt_pk_bf16_f32 v46, v38, v39
	v_add_u32_e32 v38, 0x3000, v198
	v_cvt_pk_bf16_f32 v45, v47, v48
	v_cvt_pk_bf16_f32 v47, v49, v50
	ds_read2_b64 v[48:51], v38 offset0:192 offset1:194
	v_fma_f32 v39, v40, s34, -v158
	s_waitcnt lgkmcnt(1)
	v_mfma_f32_32x32x16_bf16 v[2:17], v[34:37], v[44:47], v[2:17]
	v_fma_f32 v34, v41, s34, -v158
	v_exp_f32_e32 v58, v34
	v_fma_f32 v34, v42, s34, -v158
	v_exp_f32_e32 v59, v34
	v_fma_f32 v34, v43, s34, -v158
	v_exp_f32_e32 v60, v34
	ds_read2_b64 v[34:37], v56 offset0:132 offset1:134
	s_waitcnt lgkmcnt(1)
	v_mfma_f32_32x32x16_bf16 v[18:33], v[48:51], v[44:47], v[18:33]
	v_exp_f32_e32 v46, v39
	ds_read2_b64 v[38:41], v38 offset0:196 offset1:198
	v_cvt_pk_bf16_f32 v42, v52, v53
	v_cvt_pk_bf16_f32 v43, v54, v57
	v_cvt_pk_bf16_f32 v44, v58, v59
	v_cvt_pk_bf16_f32 v45, v60, v46
	s_waitcnt lgkmcnt(0)
	s_nop 0
	v_mfma_f32_32x32x16_bf16 v[18:33], v[38:41], v[42:45], v[18:33]
	v_mfma_f32_32x32x16_bf16 v[2:17], v[34:37], v[42:45], v[2:17]
	v_add_f32_e32 v34, v54, v55
	v_add_f32_e32 v34, v57, v34
	v_add_f32_e32 v34, v58, v34
	v_add_f32_e32 v34, v59, v34
	v_add_f32_e32 v34, v60, v34
	v_add_f32_e32 v160, v46, v34
	s_nop 4
	v_fmac_f32_e32 v160, v159, v0
.LBB0_1013:
	s_branch .LBB0_1015
.LBB0_1014:
	v_mov_b32_e32 v160, v159
	v_mov_b32_e32 v158, v157

; DI unsigned pack2(float a, float b) { f32x2 v = {a, b}; bf16x2_t r = __builtin_convertvector(v, bf16x2_t); return __builtin_bit_cast(unsigned, r); }
; DI f32x16 mfma32(bf16x8 a, bf16x8 b, f32x16 c) { return __builtin_amdgcn_mfma_f32_32x32x16_bf16(a, b, c, 0, 0, 0); }
;     ...
;   const float mn = fmaxf(m, mx); const float alpha = __builtin_amdgcn_exp2f(m - mn);
;   const float neg = (MODE == 2 && !lanesel) ? NINF : -mn;
;   float ps = 0.f;
; #pragma unroll
;   for (int k2 = 0; k2 < 2; ++k2)
; #pragma unroll
;     for (int i = 0; i < 16; ++i) {
;       if (!(HM & (1 << k2))) continue;
;       const float pv = (MODE == 1) ? __builtin_amdgcn_exp2f(s[k2][i] + neg) : __builtin_amdgcn_exp2f(fmaf(s[k2][i], L2E, neg));
;       s[k2][i] = pv; ps += pv;
;     }
;   l = l * alpha + ps;
;   if (__builtin_amdgcn_ballot_w64(mn != m) != 0ull) {
; #pragma unroll
;     for (int dt = 0; dt < 2; ++dt)
; #pragma unroll
;       for (int i = 0; i < 16; ++i) o[dt][i] *= alpha;
;   }
;   m = mn;
; #pragma unroll
;   for (int st = 0; st < 4; ++st) {
;     if (!(HM & (1 << (st >> 1)))) continue;
;     const int k2 = st >> 1, b8 = 8 * (st & 1);
;     const u32x4 pw = {pack2(s[k2][b8], s[k2][b8 + 1]), pack2(s[k2][b8 + 2], s[k2][b8 + 3]), pack2(s[k2][b8 + 4], s[k2][b8 + 5]), pack2(s[k2][b8 + 6], s[k2][b8 + 7])};
;     const bf16x8 pb = __builtin_bit_cast(bf16x8, pw);
; #pragma unroll
;     for (int dt = 0; dt < 2; ++dt) {
;       const s16x4 lo = *(const s16x4*)(Vs + (32 * dt + r) * LSTR + 16 * st + 4 * h);
;       const s16x4 hi = *(const s16x4*)(Vs + (32 * dt + r) * LSTR + 16 * st + 8 + 4 * h);
;       const bf16x8 a = __builtin_shufflevector(lo, hi, 0, 1, 2, 3, 4, 5, 6, 7);
;       o[dt] = mfma32(a, pb, o[dt]);
;     }
;   }
.LBB0_1040:
	v_fma_f32 v34, v34, s34, -v157
	v_exp_f32_e32 v46, v34
	v_fma_f32 v34, v35, s34, -v157
	v_exp_f32_e32 v47, v34
	v_fma_f32 v34, v36, s34, -v157
	v_exp_f32_e32 v48, v34
	v_fma_f32 v34, v37, s34, -v157
	v_add_f32_e32 v35, 0, v46
	v_exp_f32_e32 v49, v34
	v_fma_f32 v34, v38, s34, -v157
	v_add_f32_e32 v35, v47, v35
	v_exp_f32_e32 v38, v34
	v_fma_f32 v34, v39, s34, -v157
	v_exp_f32_e32 v39, v34
	v_add_f32_e32 v34, v48, v35
	v_fma_f32 v35, v50, s34, -v157
	v_exp_f32_e32 v50, v35
	v_fma_f32 v35, v51, s34, -v157
	v_add_f32_e32 v34, v49, v34
	v_exp_f32_e32 v51, v35
	v_fma_f32 v35, v52, s34, -v157
	v_add_f32_e32 v34, v38, v34
	v_exp_f32_e32 v52, v35
	v_fma_f32 v35, v53, s34, -v157
	v_add_f32_e32 v34, v39, v34
	v_exp_f32_e32 v53, v35
	v_add_f32_e32 v34, v50, v34
	v_add_f32_e32 v34, v51, v34
	v_add_f32_e32 v34, v52, v34
	v_add_f32_e32 v54, v53, v34
	v_fma_f32 v34, v44, s34, -v157
	v_fma_f32 v44, v45, s34, -v157
	v_add_u32_e32 v56, 0x6800, v198
	v_exp_f32_e32 v55, v34
	ds_read2_b64 v[34:37], v56 offset0:128 offset1:130
	v_exp_f32_e32 v57, v44
	v_cvt_pk_bf16_f32 v44, v46, v47
	v_cvt_pk_bf16_f32 v46, v38, v39
	v_add_u32_e32 v38, v199, v200
	v_add_u32_e32 v38, 0x7800, v38
	v_cvt_pk_bf16_f32 v45, v48, v49
	v_cvt_pk_bf16_f32 v47, v50, v51
	ds_read2_b64 v[48:51], v38 offset0:192 offset1:194
	v_fma_f32 v39, v40, s34, -v157
	s_waitcnt lgkmcnt(1)
	v_mfma_f32_32x32x16_bf16 v[2:17], v[34:37], v[44:47], v[2:17]
	v_fma_f32 v34, v41, s34, -v157
	v_exp_f32_e32 v58, v34
	v_fma_f32 v34, v42, s34, -v157
	v_exp_f32_e32 v59, v34
	v_fma_f32 v34, v43, s34, -v157
	v_exp_f32_e32 v60, v34
	ds_read2_b64 v[34:37], v56 offset0:132 offset1:134
	s_waitcnt lgkmcnt(1)
	v_mfma_f32_32x32x16_bf16 v[18:33], v[48:51], v[44:47], v[18:33]
	v_exp_f32_e32 v46, v39
	ds_read2_b64 v[38:41], v38 offset0:196 offset1:198
	v_cvt_pk_bf16_f32 v42, v52, v53
	v_cvt_pk_bf16_f32 v43, v55, v57
	v_cvt_pk_bf16_f32 v44, v58, v59
	v_cvt_pk_bf16_f32 v45, v60, v46
	s_waitcnt lgkmcnt(0)
	s_nop 0
	v_mfma_f32_32x32x16_bf16 v[18:33], v[38:41], v[42:45], v[18:33]
	v_mfma_f32_32x32x16_bf16 v[2:17], v[34:37], v[42:45], v[2:17]
	v_add_f32_e32 v34, v55, v54
	v_add_f32_e32 v34, v57, v34
	v_add_f32_e32 v34, v58, v34
	v_add_f32_e32 v34, v59, v34
	v_add_f32_e32 v34, v60, v34
	v_add_f32_e32 v159, v46, v34
	s_nop 4
	v_fmac_f32_e32 v159, v160, v0
.LBB0_1041:
	s_branch .LBB0_1043
.LBB0_1042:
	v_mov_b32_e32 v159, v160
	v_mov_b32_e32 v157, v158
